# GMIN/GLAIN/SSMIN epilogues: the 8 per-block stats loads issued together at the first block (no per-block vmcnt(0) drain)
# baseline (speedup 1.0000x reference)
; DI unsigned pk2(float lo, float hi) { const f32x2v v = {lo, hi}; const bf16x2v b = __builtin_convertvector(v, bf16x2v); return __builtin_bit_cast(unsigned, b); }
; DI float rs_of(float ss, float inv_n) { return __builtin_amdgcn_rsqf(ss * inv_n + EPS); }
; DI float sum16_fq(const float* p, int fq) { const f32x4 a = *(const f32x4*)(p + 4 * fq); float s = (a[0] + a[1]) + (a[2] + a[3]); s += __shfl_xor(s, 16); s += __shfl_xor(s, 32); return s; }
; DI void epilogue(int kind, int l, const f32x4 (&acc)[2][2][4][2], const Unit& u, int wr, int wc, int fr, int fq) {
;     ...
;     } else if (E.mode == EM_GLAIN) {
; #pragma unroll
;         for (int ai = 0; ai < 2; ++ai)
; #pragma unroll
;             for (int m = 0; m < 4; ++m) { const int row = row0 + ai * HALF + m * 16; float rs = rs_of(sum16_fq(E.ss_in + (size_t)row * 16, fq), 1.f / 1024.f);
;                 if (u.pn < 2) rs *= 0.08838834764831845f;
; #pragma unroll
;                 for (int bj = 0; bj < 2; ++bj) { const int col = col0 + bj * HALF; const f32x4 v0 = acc[ai][bj][m][0] * rs, v1 = acc[ai][bj][m][1] * rs;
;                     if (col < 3072) { u32x4 w; w.x = pk2(v0[0], v0[1]); w.y = pk2(v0[2], v0[3]); w.z = pk2(v1[0], v1[1]); w.w = pk2(v1[2], v1[3]);
;                         *(u32x4*)(E.o0 + (size_t)row * 3072 + col) = w; }
;                     else if (col < 3088) { float* tp = E.f0 + (size_t)row * 16 + (col - 3072); *(f32x4*)tp = v0; *(f32x4*)(tp + 4) = v1; } } }
.LBB0_296:
	s_lshl_b32 s42, s64, 8
	s_or_b32 s93, s42, s46
	s_mov_b64 s[18:19], -1
	v_lshl_add_u32 v172, s44, 8, v212
	s_andn2_b64 vcc, exec, s[20:21]
	v_or_b32_e32 v174, s93, v213
	s_cbranch_vccz .LBB0_811
	s_xor_b64 s[20:21], s[22:23], -1
	s_and_b64 vcc, exec, s[20:21]
	s_cbranch_vccz .LBB0_665
	s_mov_b64 s[20:21], -1
	s_mov_b64 s[18:19], 0
	s_cmp_lt_i32 s68, 4
	s_mov_b64 s[46:47], 0
	s_cbranch_scc1 .LBB0_506
	s_cmp_gt_i32 s68, 4
	s_cbranch_scc0 .LBB0_399
	s_cmp_eq_u32 s68, 5
	s_mov_b64 s[46:47], -1
	s_cbranch_scc0 .LBB0_398
	v_lshlrev_b32_e32 v24, 2, v166
	v_ashrrev_i32_e32 v173, 31, v172
	v_lshl_add_u64 v[138:139], s[88:89], 0, v[24:25]
	v_lshlrev_b64 v[134:135], 6, v[172:173]
	v_lshl_add_u64 v[130:131], v[138:139], 0, v[134:135]
	global_load_dwordx4 v[216:219], v[130:131], off
	global_load_dwordx4 v[220:223], v[130:131], off offset:1024
	global_load_dwordx4 v[224:227], v[130:131], off offset:2048
	global_load_dwordx4 v[228:231], v[130:131], off offset:3072
	v_mov_b32_e32 v250, 0x2000
	v_mov_b32_e32 v251, 0
	v_lshl_add_u64 v[248:249], v[130:131], 0, v[250:251]
	global_load_dwordx4 v[232:235], v[248:249], off
	global_load_dwordx4 v[236:239], v[248:249], off offset:1024
	global_load_dwordx4 v[240:243], v[248:249], off offset:2048
	global_load_dwordx4 v[244:247], v[248:249], off offset:3072
	v_and_b32_e32 v136, 64, v187
	v_xor_b32_e32 v24, 16, v187
	v_add_u32_e32 v140, 64, v136
	v_cmp_lt_i32_e32 vcc, v24, v140
	s_cmp_lt_i32 s64, 2
	s_cselect_b64 s[46:47], -1, 0
	v_cndmask_b32_e32 v24, v187, v24, vcc
	v_lshlrev_b32_e32 v146, 2, v24
	s_movk_i32 s20, 0xbff
	v_cmp_lt_i32_e64 s[42:43], s20, v174
	s_waitcnt vmcnt(0)
	v_mov_b32_e32 v130, v216
	v_mov_b32_e32 v131, v217
	v_mov_b32_e32 v132, v218
	v_mov_b32_e32 v133, v219
	v_mov_b32_e32 v136, v131
	v_mov_b32_e32 v137, v132
	v_mov_b32_e32 v131, v133
	v_pk_add_f32 v[130:131], v[136:137], v[130:131]
	s_nop 0
	v_add_f32_e32 v24, v130, v131
	ds_bpermute_b32 v130, v146, v24
	v_xor_b32_e32 v131, 32, v187
	v_cmp_lt_i32_e32 vcc, v131, v140
	v_lshl_add_u64 v[140:141], s[16:17], 0, v[134:135]
	s_waitcnt lgkmcnt(0)
	v_add_f32_e32 v24, v24, v130
	v_cndmask_b32_e32 v131, v187, v131, vcc
	v_lshlrev_b32_e32 v147, 2, v131
	ds_bpermute_b32 v130, v147, v24
	s_waitcnt lgkmcnt(0)
	v_add_f32_e32 v24, v24, v130
	v_fmamk_f32 v24, v24, 0x3a800000, v185
	v_rsq_f32_e32 v24, v24
	s_nop 0
	v_mul_f32_e32 v130, 0x3db504f3, v24
	v_cndmask_b32_e64 v142, v24, v130, s[46:47]
	v_pk_mul_f32 v[132:133], v[128:129], v[142:143] op_sel_hi:[1,0]
	v_pk_mul_f32 v[130:131], v[126:127], v[142:143] op_sel_hi:[1,0]
	v_pk_mul_f32 v[136:137], v[124:125], v[142:143] op_sel_hi:[1,0]
	v_pk_mul_f32 v[134:135], v[122:123], v[142:143] op_sel_hi:[1,0]
	s_and_saveexec_b64 s[20:21], s[42:43]
	s_xor_b64 s[20:21], exec, s[20:21]
	s_cbranch_execz .LBB0_305
	s_movk_i32 s22, 0xc10
	v_cmp_gt_u32_e32 vcc, s22, v174
	s_and_saveexec_b64 s[22:23], vcc
	s_cbranch_execz .LBB0_304
	v_mov_b32_e32 v175, v25
	v_lshl_add_u64 v[144:145], v[174:175], 2, v[140:141]
	v_add_co_u32_e32 v148, vcc, 0xffffd000, v144
	s_nop 1
	v_addc_co_u32_e32 v149, vcc, -1, v145, vcc
	global_store_dwordx4 v[148:149], v[130:133], off
	s_nop 1
	v_add_co_u32_e32 v130, vcc, 0xffffe000, v144
	s_nop 1
	v_addc_co_u32_e32 v131, vcc, -1, v145, vcc
	global_store_dwordx4 v[130:131], v[134:137], off offset:-4080

; DI unsigned pk2(float lo, float hi) { const f32x2v v = {lo, hi}; const bf16x2v b = __builtin_convertvector(v, bf16x2v); return __builtin_bit_cast(unsigned, b); }
; DI float rs_of(float ss, float inv_n) { return __builtin_amdgcn_rsqf(ss * inv_n + EPS); }
; DI float sum16_fq(const float* p, int fq) { const f32x4 a = *(const f32x4*)(p + 4 * fq); float s = (a[0] + a[1]) + (a[2] + a[3]); s += __shfl_xor(s, 16); s += __shfl_xor(s, 32); return s; }
; DI void epilogue(int kind, int l, const f32x4 (&acc)[2][2][4][2], const Unit& u, int wr, int wc, int fr, int fq) {
;     ...
;             for (int m = 0; m < 4; ++m) { const int row = row0 + ai * HALF + m * 16; float rs = rs_of(sum16_fq(E.ss_in + (size_t)row * 16, fq), 1.f / 1024.f);
;                 if (u.pn < 2) rs *= 0.08838834764831845f;
; #pragma unroll
;                 for (int bj = 0; bj < 2; ++bj) { const int col = col0 + bj * HALF; const f32x4 v0 = acc[ai][bj][m][0] * rs, v1 = acc[ai][bj][m][1] * rs;
;                     if (col < 3072) { u32x4 w; w.x = pk2(v0[0], v0[1]); w.y = pk2(v0[2], v0[3]); w.z = pk2(v1[0], v1[1]); w.w = pk2(v1[2], v1[3]);
;                         *(u32x4*)(E.o0 + (size_t)row * 3072 + col) = w; }
;                     else if (col < 3088) { float* tp = E.f0 + (size_t)row * 16 + (col - 3072); *(f32x4*)tp = v0; *(f32x4*)(tp + 4) = v1; } } }
.LBB0_313:
	s_or_b64 exec, exec, s[20:21]
	v_or_b32_e32 v144, 16, v172
	v_ashrrev_i32_e32 v145, 31, v144
	v_lshlrev_b64 v[134:135], 6, v[144:145]
	v_lshl_add_u64 v[130:131], v[138:139], 0, v[134:135]
	v_mov_b32_e32 v130, v220
	v_mov_b32_e32 v131, v221
	v_mov_b32_e32 v132, v222
	v_mov_b32_e32 v133, v223
	v_lshl_add_u64 v[140:141], s[16:17], 0, v[134:135]
	v_mov_b32_e32 v136, v131
	v_mov_b32_e32 v137, v132
	v_mov_b32_e32 v131, v133
	v_pk_add_f32 v[130:131], v[136:137], v[130:131]
	s_nop 0
	v_add_f32_e32 v130, v130, v131
	ds_bpermute_b32 v131, v146, v130
	s_waitcnt lgkmcnt(0)
	v_add_f32_e32 v130, v130, v131
	ds_bpermute_b32 v131, v147, v130
	s_waitcnt lgkmcnt(0)
	v_add_f32_e32 v130, v130, v131
	v_fmamk_f32 v130, v130, 0x3a800000, v185
	v_rsq_f32_e32 v130, v130
	s_nop 0
	v_mul_f32_e32 v131, 0x3db504f3, v130
	v_cndmask_b32_e64 v142, v130, v131, s[46:47]
	v_pk_mul_f32 v[132:133], v[112:113], v[142:143] op_sel_hi:[1,0]
	v_pk_mul_f32 v[130:131], v[110:111], v[142:143] op_sel_hi:[1,0]
	v_pk_mul_f32 v[136:137], v[108:109], v[142:143] op_sel_hi:[1,0]
	v_pk_mul_f32 v[134:135], v[106:107], v[142:143] op_sel_hi:[1,0]
	s_and_saveexec_b64 s[20:21], s[42:43]
	s_xor_b64 s[20:21], exec, s[20:21]
	s_cbranch_execz .LBB0_317
	s_movk_i32 s22, 0xc10
	v_cmp_gt_u32_e32 vcc, s22, v174
	s_and_saveexec_b64 s[22:23], vcc
	s_cbranch_execz .LBB0_316
	v_mov_b32_e32 v175, v25
	v_lshl_add_u64 v[148:149], v[174:175], 2, v[140:141]
	v_add_co_u32_e32 v150, vcc, 0xffffd000, v148
	s_nop 1
	v_addc_co_u32_e32 v151, vcc, -1, v149, vcc
	global_store_dwordx4 v[150:151], v[130:133], off
	s_nop 1
	v_add_co_u32_e32 v130, vcc, 0xffffe000, v148
	s_nop 1
	v_addc_co_u32_e32 v131, vcc, -1, v149, vcc
	global_store_dwordx4 v[130:131], v[134:137], off offset:-4080

; DI unsigned pk2(float lo, float hi) { const f32x2v v = {lo, hi}; const bf16x2v b = __builtin_convertvector(v, bf16x2v); return __builtin_bit_cast(unsigned, b); }
; DI float rs_of(float ss, float inv_n) { return __builtin_amdgcn_rsqf(ss * inv_n + EPS); }
; DI float sum16_fq(const float* p, int fq) { const f32x4 a = *(const f32x4*)(p + 4 * fq); float s = (a[0] + a[1]) + (a[2] + a[3]); s += __shfl_xor(s, 16); s += __shfl_xor(s, 32); return s; }
; DI void epilogue(int kind, int l, const f32x4 (&acc)[2][2][4][2], const Unit& u, int wr, int wc, int fr, int fq) {
;     ...
;             for (int m = 0; m < 4; ++m) { const int row = row0 + ai * HALF + m * 16; float rs = rs_of(sum16_fq(E.ss_in + (size_t)row * 16, fq), 1.f / 1024.f);
;                 if (u.pn < 2) rs *= 0.08838834764831845f;
; #pragma unroll
;                 for (int bj = 0; bj < 2; ++bj) { const int col = col0 + bj * HALF; const f32x4 v0 = acc[ai][bj][m][0] * rs, v1 = acc[ai][bj][m][1] * rs;
;                     if (col < 3072) { u32x4 w; w.x = pk2(v0[0], v0[1]); w.y = pk2(v0[2], v0[3]); w.z = pk2(v1[0], v1[1]); w.w = pk2(v1[2], v1[3]);
;                         *(u32x4*)(E.o0 + (size_t)row * 3072 + col) = w; }
;                     else if (col < 3088) { float* tp = E.f0 + (size_t)row * 16 + (col - 3072); *(f32x4*)tp = v0; *(f32x4*)(tp + 4) = v1; } } }
.LBB0_325:
	s_or_b64 exec, exec, s[20:21]
	v_or_b32_e32 v144, 32, v172
	v_ashrrev_i32_e32 v145, 31, v144
	v_lshlrev_b64 v[134:135], 6, v[144:145]
	v_lshl_add_u64 v[130:131], v[138:139], 0, v[134:135]
	v_mov_b32_e32 v130, v224
	v_mov_b32_e32 v131, v225
	v_mov_b32_e32 v132, v226
	v_mov_b32_e32 v133, v227
	v_lshl_add_u64 v[140:141], s[16:17], 0, v[134:135]
	v_mov_b32_e32 v136, v131
	v_mov_b32_e32 v137, v132
	v_mov_b32_e32 v131, v133
	v_pk_add_f32 v[130:131], v[136:137], v[130:131]
	s_nop 0
	v_add_f32_e32 v130, v130, v131
	ds_bpermute_b32 v131, v146, v130
	s_waitcnt lgkmcnt(0)
	v_add_f32_e32 v130, v130, v131
	ds_bpermute_b32 v131, v147, v130
	s_waitcnt lgkmcnt(0)
	v_add_f32_e32 v130, v130, v131
	v_fmamk_f32 v130, v130, 0x3a800000, v185
	v_rsq_f32_e32 v130, v130
	s_nop 0
	v_mul_f32_e32 v131, 0x3db504f3, v130
	v_cndmask_b32_e64 v142, v130, v131, s[46:47]
	v_pk_mul_f32 v[132:133], v[96:97], v[142:143] op_sel_hi:[1,0]
	v_pk_mul_f32 v[130:131], v[94:95], v[142:143] op_sel_hi:[1,0]
	v_pk_mul_f32 v[136:137], v[92:93], v[142:143] op_sel_hi:[1,0]
	v_pk_mul_f32 v[134:135], v[90:91], v[142:143] op_sel_hi:[1,0]
	s_and_saveexec_b64 s[20:21], s[42:43]
	s_xor_b64 s[20:21], exec, s[20:21]
	s_cbranch_execz .LBB0_329
	s_movk_i32 s22, 0xc10
	v_cmp_gt_u32_e32 vcc, s22, v174
	s_and_saveexec_b64 s[22:23], vcc
	s_cbranch_execz .LBB0_328
	v_mov_b32_e32 v175, v25
	v_lshl_add_u64 v[148:149], v[174:175], 2, v[140:141]
	v_add_co_u32_e32 v150, vcc, 0xffffd000, v148
	s_nop 1
	v_addc_co_u32_e32 v151, vcc, -1, v149, vcc
	global_store_dwordx4 v[150:151], v[130:133], off
	s_nop 1
	v_add_co_u32_e32 v130, vcc, 0xffffe000, v148
	s_nop 1
	v_addc_co_u32_e32 v131, vcc, -1, v149, vcc
	global_store_dwordx4 v[130:131], v[134:137], off offset:-4080

; DI unsigned pk2(float lo, float hi) { const f32x2v v = {lo, hi}; const bf16x2v b = __builtin_convertvector(v, bf16x2v); return __builtin_bit_cast(unsigned, b); }
; DI float rs_of(float ss, float inv_n) { return __builtin_amdgcn_rsqf(ss * inv_n + EPS); }
; DI float sum16_fq(const float* p, int fq) { const f32x4 a = *(const f32x4*)(p + 4 * fq); float s = (a[0] + a[1]) + (a[2] + a[3]); s += __shfl_xor(s, 16); s += __shfl_xor(s, 32); return s; }
; DI void epilogue(int kind, int l, const f32x4 (&acc)[2][2][4][2], const Unit& u, int wr, int wc, int fr, int fq) {
;     ...
;             for (int m = 0; m < 4; ++m) { const int row = row0 + ai * HALF + m * 16; float rs = rs_of(sum16_fq(E.ss_in + (size_t)row * 16, fq), 1.f / 1024.f);
;                 if (u.pn < 2) rs *= 0.08838834764831845f;
; #pragma unroll
;                 for (int bj = 0; bj < 2; ++bj) { const int col = col0 + bj * HALF; const f32x4 v0 = acc[ai][bj][m][0] * rs, v1 = acc[ai][bj][m][1] * rs;
;                     if (col < 3072) { u32x4 w; w.x = pk2(v0[0], v0[1]); w.y = pk2(v0[2], v0[3]); w.z = pk2(v1[0], v1[1]); w.w = pk2(v1[2], v1[3]);
;                         *(u32x4*)(E.o0 + (size_t)row * 3072 + col) = w; }
;                     else if (col < 3088) { float* tp = E.f0 + (size_t)row * 16 + (col - 3072); *(f32x4*)tp = v0; *(f32x4*)(tp + 4) = v1; } } }
.LBB0_337:
	s_or_b64 exec, exec, s[20:21]
	v_or_b32_e32 v144, 48, v172
	v_ashrrev_i32_e32 v145, 31, v144
	v_lshlrev_b64 v[134:135], 6, v[144:145]
	v_lshl_add_u64 v[130:131], v[138:139], 0, v[134:135]
	v_mov_b32_e32 v130, v228
	v_mov_b32_e32 v131, v229
	v_mov_b32_e32 v132, v230
	v_mov_b32_e32 v133, v231
	v_lshl_add_u64 v[140:141], s[16:17], 0, v[134:135]
	v_mov_b32_e32 v136, v131
	v_mov_b32_e32 v137, v132
	v_mov_b32_e32 v131, v133
	v_pk_add_f32 v[130:131], v[136:137], v[130:131]
	s_nop 0
	v_add_f32_e32 v130, v130, v131
	ds_bpermute_b32 v131, v146, v130
	s_waitcnt lgkmcnt(0)
	v_add_f32_e32 v130, v130, v131
	ds_bpermute_b32 v131, v147, v130
	s_waitcnt lgkmcnt(0)
	v_add_f32_e32 v130, v130, v131
	v_fmamk_f32 v130, v130, 0x3a800000, v185
	v_rsq_f32_e32 v130, v130
	s_nop 0
	v_mul_f32_e32 v131, 0x3db504f3, v130
	v_cndmask_b32_e64 v142, v130, v131, s[46:47]
	v_pk_mul_f32 v[132:133], v[80:81], v[142:143] op_sel_hi:[1,0]
	v_pk_mul_f32 v[130:131], v[78:79], v[142:143] op_sel_hi:[1,0]
	v_pk_mul_f32 v[136:137], v[76:77], v[142:143] op_sel_hi:[1,0]
	v_pk_mul_f32 v[134:135], v[74:75], v[142:143] op_sel_hi:[1,0]
	s_and_saveexec_b64 s[20:21], s[42:43]
	s_xor_b64 s[20:21], exec, s[20:21]
	s_cbranch_execz .LBB0_341
	s_movk_i32 s22, 0xc10
	v_cmp_gt_u32_e32 vcc, s22, v174
	s_and_saveexec_b64 s[22:23], vcc
	s_cbranch_execz .LBB0_340
	v_mov_b32_e32 v175, v25
	v_lshl_add_u64 v[148:149], v[174:175], 2, v[140:141]
	v_add_co_u32_e32 v150, vcc, 0xffffd000, v148
	s_nop 1
	v_addc_co_u32_e32 v151, vcc, -1, v149, vcc
	global_store_dwordx4 v[150:151], v[130:133], off
	s_nop 1
	v_add_co_u32_e32 v130, vcc, 0xffffe000, v148
	s_nop 1
	v_addc_co_u32_e32 v131, vcc, -1, v149, vcc
	global_store_dwordx4 v[130:131], v[134:137], off offset:-4080

; DI unsigned pk2(float lo, float hi) { const f32x2v v = {lo, hi}; const bf16x2v b = __builtin_convertvector(v, bf16x2v); return __builtin_bit_cast(unsigned, b); }
; DI float rs_of(float ss, float inv_n) { return __builtin_amdgcn_rsqf(ss * inv_n + EPS); }
; DI float sum16_fq(const float* p, int fq) { const f32x4 a = *(const f32x4*)(p + 4 * fq); float s = (a[0] + a[1]) + (a[2] + a[3]); s += __shfl_xor(s, 16); s += __shfl_xor(s, 32); return s; }
; DI void epilogue(int kind, int l, const f32x4 (&acc)[2][2][4][2], const Unit& u, int wr, int wc, int fr, int fq) {
;     ...
;             for (int m = 0; m < 4; ++m) { const int row = row0 + ai * HALF + m * 16; float rs = rs_of(sum16_fq(E.ss_in + (size_t)row * 16, fq), 1.f / 1024.f);
;                 if (u.pn < 2) rs *= 0.08838834764831845f;
; #pragma unroll
;                 for (int bj = 0; bj < 2; ++bj) { const int col = col0 + bj * HALF; const f32x4 v0 = acc[ai][bj][m][0] * rs, v1 = acc[ai][bj][m][1] * rs;
;                     if (col < 3072) { u32x4 w; w.x = pk2(v0[0], v0[1]); w.y = pk2(v0[2], v0[3]); w.z = pk2(v1[0], v1[1]); w.w = pk2(v1[2], v1[3]);
;                         *(u32x4*)(E.o0 + (size_t)row * 3072 + col) = w; }
;                     else if (col < 3088) { float* tp = E.f0 + (size_t)row * 16 + (col - 3072); *(f32x4*)tp = v0; *(f32x4*)(tp + 4) = v1; } } }
.LBB0_349:
	s_or_b64 exec, exec, s[20:21]
	v_add_u32_e32 v144, 0x80, v172
	v_ashrrev_i32_e32 v145, 31, v144
	v_lshlrev_b64 v[134:135], 6, v[144:145]
	v_lshl_add_u64 v[130:131], v[138:139], 0, v[134:135]
	v_mov_b32_e32 v130, v232
	v_mov_b32_e32 v131, v233
	v_mov_b32_e32 v132, v234
	v_mov_b32_e32 v133, v235
	v_lshl_add_u64 v[140:141], s[16:17], 0, v[134:135]
	v_mov_b32_e32 v136, v131
	v_mov_b32_e32 v137, v132
	v_mov_b32_e32 v131, v133
	v_pk_add_f32 v[130:131], v[136:137], v[130:131]
	s_nop 0
	v_add_f32_e32 v130, v130, v131
	ds_bpermute_b32 v131, v146, v130
	s_waitcnt lgkmcnt(0)
	v_add_f32_e32 v130, v130, v131
	ds_bpermute_b32 v131, v147, v130
	s_waitcnt lgkmcnt(0)
	v_add_f32_e32 v130, v130, v131
	v_fmamk_f32 v130, v130, 0x3a800000, v185
	v_rsq_f32_e32 v130, v130
	s_nop 0
	v_mul_f32_e32 v131, 0x3db504f3, v130
	v_cndmask_b32_e64 v142, v130, v131, s[46:47]
	v_pk_mul_f32 v[132:133], v[64:65], v[142:143] op_sel_hi:[1,0]
	v_pk_mul_f32 v[130:131], v[62:63], v[142:143] op_sel_hi:[1,0]
	v_pk_mul_f32 v[136:137], v[60:61], v[142:143] op_sel_hi:[1,0]
	v_pk_mul_f32 v[134:135], v[58:59], v[142:143] op_sel_hi:[1,0]
	s_and_saveexec_b64 s[20:21], s[42:43]
	s_xor_b64 s[20:21], exec, s[20:21]
	s_cbranch_execz .LBB0_353
	s_movk_i32 s22, 0xc10
	v_cmp_gt_u32_e32 vcc, s22, v174
	s_and_saveexec_b64 s[22:23], vcc
	s_cbranch_execz .LBB0_352
	v_mov_b32_e32 v175, v25
	v_lshl_add_u64 v[148:149], v[174:175], 2, v[140:141]
	v_add_co_u32_e32 v150, vcc, 0xffffd000, v148
	s_nop 1
	v_addc_co_u32_e32 v151, vcc, -1, v149, vcc
	global_store_dwordx4 v[150:151], v[130:133], off
	s_nop 1
	v_add_co_u32_e32 v130, vcc, 0xffffe000, v148
	s_nop 1
	v_addc_co_u32_e32 v131, vcc, -1, v149, vcc
	global_store_dwordx4 v[130:131], v[134:137], off offset:-4080

; DI unsigned pk2(float lo, float hi) { const f32x2v v = {lo, hi}; const bf16x2v b = __builtin_convertvector(v, bf16x2v); return __builtin_bit_cast(unsigned, b); }
; DI float rs_of(float ss, float inv_n) { return __builtin_amdgcn_rsqf(ss * inv_n + EPS); }
; DI float sum16_fq(const float* p, int fq) { const f32x4 a = *(const f32x4*)(p + 4 * fq); float s = (a[0] + a[1]) + (a[2] + a[3]); s += __shfl_xor(s, 16); s += __shfl_xor(s, 32); return s; }
; DI void epilogue(int kind, int l, const f32x4 (&acc)[2][2][4][2], const Unit& u, int wr, int wc, int fr, int fq) {
;     ...
;             for (int m = 0; m < 4; ++m) { const int row = row0 + ai * HALF + m * 16; float rs = rs_of(sum16_fq(E.ss_in + (size_t)row * 16, fq), 1.f / 1024.f);
;                 if (u.pn < 2) rs *= 0.08838834764831845f;
; #pragma unroll
;                 for (int bj = 0; bj < 2; ++bj) { const int col = col0 + bj * HALF; const f32x4 v0 = acc[ai][bj][m][0] * rs, v1 = acc[ai][bj][m][1] * rs;
;                     if (col < 3072) { u32x4 w; w.x = pk2(v0[0], v0[1]); w.y = pk2(v0[2], v0[3]); w.z = pk2(v1[0], v1[1]); w.w = pk2(v1[2], v1[3]);
;                         *(u32x4*)(E.o0 + (size_t)row * 3072 + col) = w; }
;                     else if (col < 3088) { float* tp = E.f0 + (size_t)row * 16 + (col - 3072); *(f32x4*)tp = v0; *(f32x4*)(tp + 4) = v1; } } }
.LBB0_361:
	s_or_b64 exec, exec, s[20:21]
	v_add_u32_e32 v144, 0x90, v172
	v_ashrrev_i32_e32 v145, 31, v144
	v_lshlrev_b64 v[134:135], 6, v[144:145]
	v_lshl_add_u64 v[130:131], v[138:139], 0, v[134:135]
	v_mov_b32_e32 v130, v236
	v_mov_b32_e32 v131, v237
	v_mov_b32_e32 v132, v238
	v_mov_b32_e32 v133, v239
	v_lshl_add_u64 v[140:141], s[16:17], 0, v[134:135]
	v_mov_b32_e32 v136, v131
	v_mov_b32_e32 v137, v132
	v_mov_b32_e32 v131, v133
	v_pk_add_f32 v[130:131], v[136:137], v[130:131]
	s_nop 0
	v_add_f32_e32 v130, v130, v131
	ds_bpermute_b32 v131, v146, v130
	s_waitcnt lgkmcnt(0)
	v_add_f32_e32 v130, v130, v131
	ds_bpermute_b32 v131, v147, v130
	s_waitcnt lgkmcnt(0)
	v_add_f32_e32 v130, v130, v131
	v_fmamk_f32 v130, v130, 0x3a800000, v185
	v_rsq_f32_e32 v130, v130
	s_nop 0
	v_mul_f32_e32 v131, 0x3db504f3, v130
	v_cndmask_b32_e64 v142, v130, v131, s[46:47]
	v_pk_mul_f32 v[132:133], v[48:49], v[142:143] op_sel_hi:[1,0]
	v_pk_mul_f32 v[130:131], v[46:47], v[142:143] op_sel_hi:[1,0]
	v_pk_mul_f32 v[136:137], v[44:45], v[142:143] op_sel_hi:[1,0]
	v_pk_mul_f32 v[134:135], v[42:43], v[142:143] op_sel_hi:[1,0]
	s_and_saveexec_b64 s[20:21], s[42:43]
	s_xor_b64 s[20:21], exec, s[20:21]
	s_cbranch_execz .LBB0_365
	s_movk_i32 s22, 0xc10
	v_cmp_gt_u32_e32 vcc, s22, v174
	s_and_saveexec_b64 s[22:23], vcc
	s_cbranch_execz .LBB0_364
	v_mov_b32_e32 v175, v25
	v_lshl_add_u64 v[148:149], v[174:175], 2, v[140:141]
	v_add_co_u32_e32 v150, vcc, 0xffffd000, v148
	s_nop 1
	v_addc_co_u32_e32 v151, vcc, -1, v149, vcc
	global_store_dwordx4 v[150:151], v[130:133], off
	s_nop 1
	v_add_co_u32_e32 v130, vcc, 0xffffe000, v148
	s_nop 1
	v_addc_co_u32_e32 v131, vcc, -1, v149, vcc
	global_store_dwordx4 v[130:131], v[134:137], off offset:-4080

; DI unsigned pk2(float lo, float hi) { const f32x2v v = {lo, hi}; const bf16x2v b = __builtin_convertvector(v, bf16x2v); return __builtin_bit_cast(unsigned, b); }
; DI float rs_of(float ss, float inv_n) { return __builtin_amdgcn_rsqf(ss * inv_n + EPS); }
; DI float sum16_fq(const float* p, int fq) { const f32x4 a = *(const f32x4*)(p + 4 * fq); float s = (a[0] + a[1]) + (a[2] + a[3]); s += __shfl_xor(s, 16); s += __shfl_xor(s, 32); return s; }
; DI void epilogue(int kind, int l, const f32x4 (&acc)[2][2][4][2], const Unit& u, int wr, int wc, int fr, int fq) {
;     ...
;             for (int m = 0; m < 4; ++m) { const int row = row0 + ai * HALF + m * 16; float rs = rs_of(sum16_fq(E.ss_in + (size_t)row * 16, fq), 1.f / 1024.f);
;                 if (u.pn < 2) rs *= 0.08838834764831845f;
; #pragma unroll
;                 for (int bj = 0; bj < 2; ++bj) { const int col = col0 + bj * HALF; const f32x4 v0 = acc[ai][bj][m][0] * rs, v1 = acc[ai][bj][m][1] * rs;
;                     if (col < 3072) { u32x4 w; w.x = pk2(v0[0], v0[1]); w.y = pk2(v0[2], v0[3]); w.z = pk2(v1[0], v1[1]); w.w = pk2(v1[2], v1[3]);
;                         *(u32x4*)(E.o0 + (size_t)row * 3072 + col) = w; }
;                     else if (col < 3088) { float* tp = E.f0 + (size_t)row * 16 + (col - 3072); *(f32x4*)tp = v0; *(f32x4*)(tp + 4) = v1; } } }
.LBB0_373:
	s_or_b64 exec, exec, s[20:21]
	v_add_u32_e32 v144, 0xa0, v172
	v_ashrrev_i32_e32 v145, 31, v144
	v_lshlrev_b64 v[134:135], 6, v[144:145]
	v_lshl_add_u64 v[130:131], v[138:139], 0, v[134:135]
	v_mov_b32_e32 v130, v240
	v_mov_b32_e32 v131, v241
	v_mov_b32_e32 v132, v242
	v_mov_b32_e32 v133, v243
	v_lshl_add_u64 v[140:141], s[16:17], 0, v[134:135]
	v_mov_b32_e32 v136, v131
	v_mov_b32_e32 v137, v132
	v_mov_b32_e32 v131, v133
	v_pk_add_f32 v[130:131], v[136:137], v[130:131]
	s_nop 0
	v_add_f32_e32 v130, v130, v131
	ds_bpermute_b32 v131, v146, v130
	s_waitcnt lgkmcnt(0)
	v_add_f32_e32 v130, v130, v131
	ds_bpermute_b32 v131, v147, v130
	s_waitcnt lgkmcnt(0)
	v_add_f32_e32 v130, v130, v131
	v_fmamk_f32 v130, v130, 0x3a800000, v185
	v_rsq_f32_e32 v130, v130
	s_nop 0
	v_mul_f32_e32 v131, 0x3db504f3, v130
	v_cndmask_b32_e64 v142, v130, v131, s[46:47]
	v_pk_mul_f32 v[132:133], v[32:33], v[142:143] op_sel_hi:[1,0]
	v_pk_mul_f32 v[130:131], v[30:31], v[142:143] op_sel_hi:[1,0]
	v_pk_mul_f32 v[136:137], v[28:29], v[142:143] op_sel_hi:[1,0]
	v_pk_mul_f32 v[134:135], v[26:27], v[142:143] op_sel_hi:[1,0]
	s_and_saveexec_b64 s[20:21], s[42:43]
	s_xor_b64 s[20:21], exec, s[20:21]
	s_cbranch_execz .LBB0_377
	s_movk_i32 s22, 0xc10
	v_cmp_gt_u32_e32 vcc, s22, v174
	s_and_saveexec_b64 s[22:23], vcc
	s_cbranch_execz .LBB0_376
	v_mov_b32_e32 v175, v25
	v_lshl_add_u64 v[148:149], v[174:175], 2, v[140:141]
	v_add_co_u32_e32 v150, vcc, 0xffffd000, v148
	s_nop 1
	v_addc_co_u32_e32 v151, vcc, -1, v149, vcc
	global_store_dwordx4 v[150:151], v[130:133], off
	s_nop 1
	v_add_co_u32_e32 v130, vcc, 0xffffe000, v148
	s_nop 1
	v_addc_co_u32_e32 v131, vcc, -1, v149, vcc
	global_store_dwordx4 v[130:131], v[134:137], off offset:-4080

; DI unsigned pk2(float lo, float hi) { const f32x2v v = {lo, hi}; const bf16x2v b = __builtin_convertvector(v, bf16x2v); return __builtin_bit_cast(unsigned, b); }
; DI float rs_of(float ss, float inv_n) { return __builtin_amdgcn_rsqf(ss * inv_n + EPS); }
; DI float sum16_fq(const float* p, int fq) { const f32x4 a = *(const f32x4*)(p + 4 * fq); float s = (a[0] + a[1]) + (a[2] + a[3]); s += __shfl_xor(s, 16); s += __shfl_xor(s, 32); return s; }
; DI void epilogue(int kind, int l, const f32x4 (&acc)[2][2][4][2], const Unit& u, int wr, int wc, int fr, int fq) {
;     ...
;             for (int m = 0; m < 4; ++m) { const int row = row0 + ai * HALF + m * 16; float rs = rs_of(sum16_fq(E.ss_in + (size_t)row * 16, fq), 1.f / 1024.f);
;                 if (u.pn < 2) rs *= 0.08838834764831845f;
; #pragma unroll
;                 for (int bj = 0; bj < 2; ++bj) { const int col = col0 + bj * HALF; const f32x4 v0 = acc[ai][bj][m][0] * rs, v1 = acc[ai][bj][m][1] * rs;
;                     if (col < 3072) { u32x4 w; w.x = pk2(v0[0], v0[1]); w.y = pk2(v0[2], v0[3]); w.z = pk2(v1[0], v1[1]); w.w = pk2(v1[2], v1[3]);
;                         *(u32x4*)(E.o0 + (size_t)row * 3072 + col) = w; }
;                     else if (col < 3088) { float* tp = E.f0 + (size_t)row * 16 + (col - 3072); *(f32x4*)tp = v0; *(f32x4*)(tp + 4) = v1; } } }
.LBB0_385:
	s_or_b64 exec, exec, s[20:21]
	v_add_u32_e32 v142, 0xb0, v172
	v_ashrrev_i32_e32 v143, 31, v142
	v_lshlrev_b64 v[134:135], 6, v[142:143]
	v_lshl_add_u64 v[130:131], v[138:139], 0, v[134:135]
	v_mov_b32_e32 v130, v244
	v_mov_b32_e32 v131, v245
	v_mov_b32_e32 v132, v246
	v_mov_b32_e32 v133, v247
	v_lshl_add_u64 v[138:139], s[16:17], 0, v[134:135]
	v_mov_b32_e32 v136, v131
	v_mov_b32_e32 v137, v132
	v_mov_b32_e32 v131, v133
	v_pk_add_f32 v[130:131], v[136:137], v[130:131]
	s_nop 0
	v_add_f32_e32 v130, v130, v131
	ds_bpermute_b32 v131, v146, v130
	s_waitcnt lgkmcnt(0)
	v_add_f32_e32 v130, v130, v131
	ds_bpermute_b32 v131, v147, v130
	s_waitcnt lgkmcnt(0)
	v_add_f32_e32 v130, v130, v131
	v_fmamk_f32 v130, v130, 0x3a800000, v185
	v_rsq_f32_e32 v130, v130
	s_nop 0
	v_mul_f32_e32 v131, 0x3db504f3, v130
	v_cndmask_b32_e64 v140, v130, v131, s[46:47]
	v_pk_mul_f32 v[132:133], v[14:15], v[140:141] op_sel_hi:[1,0]
	v_pk_mul_f32 v[130:131], v[12:13], v[140:141] op_sel_hi:[1,0]
	v_pk_mul_f32 v[136:137], v[10:11], v[140:141] op_sel_hi:[1,0]
	v_pk_mul_f32 v[134:135], v[8:9], v[140:141] op_sel_hi:[1,0]
	s_and_saveexec_b64 s[20:21], s[42:43]
	s_xor_b64 s[20:21], exec, s[20:21]
	s_cbranch_execz .LBB0_389
	s_movk_i32 s22, 0xc10
	v_cmp_gt_u32_e32 vcc, s22, v174
	s_and_saveexec_b64 s[22:23], vcc
	s_cbranch_execz .LBB0_388
	v_mov_b32_e32 v175, v25
	v_lshl_add_u64 v[144:145], v[174:175], 2, v[138:139]
	v_add_co_u32_e32 v146, vcc, 0xffffd000, v144
	s_nop 1
	v_addc_co_u32_e32 v147, vcc, -1, v145, vcc
	global_store_dwordx4 v[146:147], v[130:133], off
	s_nop 1
	v_add_co_u32_e32 v130, vcc, 0xffffe000, v144
	s_nop 1
	v_addc_co_u32_e32 v131, vcc, -1, v145, vcc
	global_store_dwordx4 v[130:131], v[134:137], off offset:-4080

; DI float geluf_(float x) { return x * sigmoidf_(1.5957691216f * (x + 0.044715f * x * x * x)); }
; DI u32x4 pack8(const float* f) { u32x4 w; w.x = pk2(f[0], f[1]); w.y = pk2(f[2], f[3]); w.z = pk2(f[4], f[5]); w.w = pk2(f[6], f[7]); return w; }
; DI float rs_of(float ss, float inv_n) { return __builtin_amdgcn_rsqf(ss * inv_n + EPS); }
; DI float sum16_fq(const float* p, int fq) { const f32x4 a = *(const f32x4*)(p + 4 * fq); float s = (a[0] + a[1]) + (a[2] + a[3]); s += __shfl_xor(s, 16); s += __shfl_xor(s, 32); return s; }
; DI void epilogue(int kind, int l, const f32x4 (&acc)[2][2][4][2], const Unit& u, int wr, int wc, int fr, int fq) {
;     ...
;             for (int m = 0; m < 4; ++m) { const int row = row0 + ai * HALF + m * 16; const float rs = rs_of(sum16_fq(E.ss_in + (size_t)row * 16, fq), 1.f / 1024.f); float s1 = 0.f, s2 = 0.f;
; #pragma unroll
;                 for (int bj = 0; bj < 2; ++bj) { const int col = col0 + bj * HALF; float v[8];
; #pragma unroll
;                     for (int j = 0; j < 4; ++j) { v[j] = geluf_(acc[ai][bj][m][0][j] * rs); v[4 + j] = geluf_(acc[ai][bj][m][1][j] * rs); }
;                     const u32x4 w = pack8(v);
;                     if (isv) { *(u32x4*)(E.o1 + (size_t)row * DM + col - 1024) = w;
; #pragma unroll
;                         for (int j = 0; j < 8; ++j) { s1 += v[j]; s2 += v[j] * v[j]; } }
;                     else *(u32x4*)(E.o0 + (size_t)row * DM + col) = w; }
.LBB0_399:
	s_and_b64 vcc, exec, s[20:21]
	s_cbranch_vccz .LBB0_505
	v_lshlrev_b32_e32 v24, 2, v166
	v_and_b32_e32 v130, 64, v187
	v_lshl_add_u64 v[134:135], s[88:89], 0, v[24:25]
	v_xor_b32_e32 v24, 16, v187
	v_add_u32_e32 v130, 64, v130
	v_cmp_lt_i32_e32 vcc, v24, v130
	v_ashrrev_i32_e32 v173, 31, v172
	s_cmp_gt_i32 s64, 3
	v_cndmask_b32_e32 v24, v187, v24, vcc
	v_lshlrev_b32_e32 v153, 2, v24
	v_xor_b32_e32 v24, 32, v187
	v_cmp_lt_i32_e32 vcc, v24, v130
	v_lshlrev_b64 v[130:131], 6, v[172:173]
	v_lshl_add_u64 v[130:131], v[134:135], 0, v[130:131]
	global_load_dwordx4 v[216:219], v[130:131], off
	global_load_dwordx4 v[220:223], v[130:131], off offset:1024
	global_load_dwordx4 v[224:227], v[130:131], off offset:2048
	global_load_dwordx4 v[228:231], v[130:131], off offset:3072
	v_mov_b32_e32 v250, 0x2000
	v_mov_b32_e32 v251, 0
	v_lshl_add_u64 v[248:249], v[130:131], 0, v[250:251]
	global_load_dwordx4 v[232:235], v[248:249], off
	global_load_dwordx4 v[236:239], v[248:249], off offset:1024
	global_load_dwordx4 v[240:243], v[248:249], off offset:2048
	global_load_dwordx4 v[244:247], v[248:249], off offset:3072
	v_cndmask_b32_e32 v24, v187, v24, vcc
	v_lshlrev_b32_e32 v152, 2, v24
	s_cselect_b64 s[22:23], -1, 0
	s_cmp_lt_i32 s64, 4
	s_cselect_b64 s[20:21], -1, 0
	v_lshlrev_b64 v[140:141], 11, v[172:173]
	s_mov_b64 s[42:43], -1
	s_and_b64 vcc, exec, s[20:21]
	s_waitcnt vmcnt(0)
	v_mov_b32_e32 v130, v216
	v_mov_b32_e32 v131, v217
	v_mov_b32_e32 v132, v218
	v_mov_b32_e32 v133, v219
	v_mov_b32_e32 v136, v131
	v_mov_b32_e32 v137, v132
	v_mov_b32_e32 v131, v133
	v_pk_add_f32 v[130:131], v[136:137], v[130:131]
	v_lshl_add_u64 v[136:137], s[78:79], 0, v[140:141]
	v_add_f32_e32 v24, v130, v131
	ds_bpermute_b32 v130, v153, v24
	s_waitcnt lgkmcnt(0)
	v_add_f32_e32 v24, v24, v130
	ds_bpermute_b32 v130, v152, v24
	s_waitcnt lgkmcnt(0)
	v_add_f32_e32 v24, v24, v130
	v_fmamk_f32 v24, v24, 0x3a800000, v185
	v_rsq_f32_e32 v138, v24
	s_nop 0
	v_pk_mul_f32 v[130:131], v[126:127], v[138:139] op_sel_hi:[1,0]
	s_nop 0
	v_mul_f32_e32 v24, 0x3d372713, v130
	v_mul_f32_e32 v24, v130, v24
	v_fma_f32 v24, v130, v24, v130
	v_mul_f32_e32 v24, 0x3fcc422a, v24
	v_mul_f32_e32 v24, 0xbfb8aa3b, v24
	v_exp_f32_e32 v24, v24
	s_nop 0
	v_add_f32_e32 v24, 1.0, v24
	v_rcp_f32_e32 v132, v24
	v_mul_f32_e32 v24, 0x3d372713, v131
	v_mul_f32_e32 v24, v131, v24
	v_fma_f32 v24, v131, v24, v131
	v_mul_f32_e32 v24, 0x3fcc422a, v24
	v_mul_f32_e32 v24, 0xbfb8aa3b, v24
	v_exp_f32_e32 v24, v24
	s_nop 0
	v_add_f32_e32 v24, 1.0, v24
	v_rcp_f32_e32 v133, v24
	s_nop 0
	v_pk_mul_f32 v[142:143], v[130:131], v[132:133]
	v_pk_mul_f32 v[130:131], v[122:123], v[138:139] op_sel_hi:[1,0]
	s_nop 0
	v_mul_f32_e32 v24, 0x3d372713, v130
	v_mul_f32_e32 v24, v130, v24
	v_fma_f32 v24, v130, v24, v130
	v_mul_f32_e32 v24, 0x3fcc422a, v24
	v_mul_f32_e32 v24, 0xbfb8aa3b, v24
	v_exp_f32_e32 v24, v24
	s_nop 0
	v_add_f32_e32 v24, 1.0, v24
	v_rcp_f32_e32 v132, v24
	v_mul_f32_e32 v24, 0x3d372713, v131
	v_mul_f32_e32 v24, v131, v24
	v_fma_f32 v24, v131, v24, v131
	v_mul_f32_e32 v24, 0x3fcc422a, v24
	v_mul_f32_e32 v24, 0xbfb8aa3b, v24
	v_exp_f32_e32 v24, v24
	s_nop 0
	v_add_f32_e32 v24, 1.0, v24
	v_rcp_f32_e32 v133, v24
	s_nop 0
	v_pk_mul_f32 v[144:145], v[130:131], v[132:133]
	v_pk_mul_f32 v[130:131], v[128:129], v[138:139] op_sel_hi:[1,0]
	s_nop 0
	v_mul_f32_e32 v24, 0x3d372713, v130
	v_mul_f32_e32 v24, v130, v24
	v_fma_f32 v24, v130, v24, v130
	v_mul_f32_e32 v24, 0x3fcc422a, v24
	v_mul_f32_e32 v24, 0xbfb8aa3b, v24
	v_exp_f32_e32 v24, v24
	s_nop 0
	v_add_f32_e32 v24, 1.0, v24
	v_rcp_f32_e32 v132, v24
	v_mul_f32_e32 v24, 0x3d372713, v131
	v_mul_f32_e32 v24, v131, v24
	v_fma_f32 v24, v131, v24, v131
	v_mul_f32_e32 v24, 0x3fcc422a, v24
	v_mul_f32_e32 v24, 0xbfb8aa3b, v24
	v_exp_f32_e32 v24, v24
	s_nop 0
	v_add_f32_e32 v24, 1.0, v24
	v_rcp_f32_e32 v133, v24
	s_nop 0
	v_pk_mul_f32 v[146:147], v[130:131], v[132:133]
	v_pk_mul_f32 v[130:131], v[124:125], v[138:139] op_sel_hi:[1,0]
	s_nop 0
	v_mul_f32_e32 v24, 0x3d372713, v130
	v_mul_f32_e32 v24, v130, v24
	v_fma_f32 v24, v130, v24, v130
	v_mul_f32_e32 v24, 0x3fcc422a, v24
	v_mul_f32_e32 v24, 0xbfb8aa3b, v24
	v_exp_f32_e32 v24, v24
	s_nop 0
	v_add_f32_e32 v24, 1.0, v24
	v_rcp_f32_e32 v132, v24
	v_mul_f32_e32 v24, 0x3d372713, v131
	v_mul_f32_e32 v24, v131, v24
	v_fma_f32 v24, v131, v24, v131
	v_mul_f32_e32 v24, 0x3fcc422a, v24
	v_mul_f32_e32 v24, 0xbfb8aa3b, v24
	v_exp_f32_e32 v24, v24
	s_nop 0
	v_add_f32_e32 v24, 1.0, v24
	v_rcp_f32_e32 v133, v24
	s_nop 0
	v_pk_mul_f32 v[148:149], v[130:131], v[132:133]
	v_cvt_pk_bf16_f32 v130, v142, v143
	v_cvt_pk_bf16_f32 v131, v146, v147
	v_cvt_pk_bf16_f32 v132, v144, v145
	v_cvt_pk_bf16_f32 v133, v148, v149
	s_cbranch_vccz .LBB0_402
	v_ashrrev_i32_e32 v175, 31, v174
	v_lshl_add_u64 v[150:151], v[174:175], 1, v[136:137]
	s_mov_b64 s[42:43], 0
	global_store_dwordx4 v[150:151], v[130:133], off

; DI float geluf_(float x) { return x * sigmoidf_(1.5957691216f * (x + 0.044715f * x * x * x)); }
; DI u32x4 pack8(const float* f) { u32x4 w; w.x = pk2(f[0], f[1]); w.y = pk2(f[2], f[3]); w.z = pk2(f[4], f[5]); w.w = pk2(f[6], f[7]); return w; }
; DI float rs_of(float ss, float inv_n) { return __builtin_amdgcn_rsqf(ss * inv_n + EPS); }
; DI float sum16_fq(const float* p, int fq) { const f32x4 a = *(const f32x4*)(p + 4 * fq); float s = (a[0] + a[1]) + (a[2] + a[3]); s += __shfl_xor(s, 16); s += __shfl_xor(s, 32); return s; }
; DI void epilogue(int kind, int l, const f32x4 (&acc)[2][2][4][2], const Unit& u, int wr, int wc, int fr, int fq) {
;     ...
;             for (int m = 0; m < 4; ++m) { const int row = row0 + ai * HALF + m * 16; const float rs = rs_of(sum16_fq(E.ss_in + (size_t)row * 16, fq), 1.f / 1024.f); float s1 = 0.f, s2 = 0.f;
; #pragma unroll
;                 for (int bj = 0; bj < 2; ++bj) { const int col = col0 + bj * HALF; float v[8];
; #pragma unroll
;                     for (int j = 0; j < 4; ++j) { v[j] = geluf_(acc[ai][bj][m][0][j] * rs); v[4 + j] = geluf_(acc[ai][bj][m][1][j] * rs); }
;                     const u32x4 w = pack8(v);
;                     if (isv) { *(u32x4*)(E.o1 + (size_t)row * DM + col - 1024) = w;
; #pragma unroll
;                         for (int j = 0; j < 8; ++j) { s1 += v[j]; s2 += v[j] * v[j]; } }
;                     else *(u32x4*)(E.o0 + (size_t)row * DM + col) = w; }
.LBB0_414:
	v_or_b32_e32 v136, 16, v172
	v_ashrrev_i32_e32 v137, 31, v136
	v_lshlrev_b64 v[130:131], 6, v[136:137]
	v_lshl_add_u64 v[130:131], v[134:135], 0, v[130:131]
	s_waitcnt lgkmcnt(0)
	v_mov_b32_e32 v130, v220
	v_mov_b32_e32 v131, v221
	v_mov_b32_e32 v132, v222
	v_mov_b32_e32 v133, v223
	v_lshlrev_b64 v[142:143], 11, v[136:137]
	s_mov_b64 s[22:23], -1
	s_and_b64 vcc, exec, s[42:43]
	v_mov_b32_e32 v138, v131
	v_mov_b32_e32 v139, v132
	v_mov_b32_e32 v131, v133
	v_pk_add_f32 v[130:131], v[138:139], v[130:131]
	v_lshl_add_u64 v[138:139], s[78:79], 0, v[142:143]
	v_add_f32_e32 v24, v130, v131
	ds_bpermute_b32 v130, v153, v24
	s_waitcnt lgkmcnt(0)
	v_add_f32_e32 v24, v24, v130
	ds_bpermute_b32 v130, v152, v24
	s_waitcnt lgkmcnt(0)
	v_add_f32_e32 v24, v24, v130
	v_fmamk_f32 v24, v24, 0x3a800000, v185
	v_rsq_f32_e32 v140, v24
	s_nop 0
	v_pk_mul_f32 v[130:131], v[110:111], v[140:141] op_sel_hi:[1,0]
	s_nop 0
	v_mul_f32_e32 v24, 0x3d372713, v130
	v_mul_f32_e32 v24, v130, v24
	v_fma_f32 v24, v130, v24, v130
	v_mul_f32_e32 v24, 0x3fcc422a, v24
	v_mul_f32_e32 v24, 0xbfb8aa3b, v24
	v_exp_f32_e32 v24, v24
	s_nop 0
	v_add_f32_e32 v24, 1.0, v24
	v_rcp_f32_e32 v132, v24
	v_mul_f32_e32 v24, 0x3d372713, v131
	v_mul_f32_e32 v24, v131, v24
	v_fma_f32 v24, v131, v24, v131
	v_mul_f32_e32 v24, 0x3fcc422a, v24
	v_mul_f32_e32 v24, 0xbfb8aa3b, v24
	v_exp_f32_e32 v24, v24
	s_nop 0
	v_add_f32_e32 v24, 1.0, v24
	v_rcp_f32_e32 v133, v24
	s_nop 0
	v_pk_mul_f32 v[144:145], v[130:131], v[132:133]
	v_pk_mul_f32 v[130:131], v[106:107], v[140:141] op_sel_hi:[1,0]
	s_nop 0
	v_mul_f32_e32 v24, 0x3d372713, v130
	v_mul_f32_e32 v24, v130, v24
	v_fma_f32 v24, v130, v24, v130
	v_mul_f32_e32 v24, 0x3fcc422a, v24
	v_mul_f32_e32 v24, 0xbfb8aa3b, v24
	v_exp_f32_e32 v24, v24
	s_nop 0
	v_add_f32_e32 v24, 1.0, v24
	v_rcp_f32_e32 v132, v24
	v_mul_f32_e32 v24, 0x3d372713, v131
	v_mul_f32_e32 v24, v131, v24
	v_fma_f32 v24, v131, v24, v131
	v_mul_f32_e32 v24, 0x3fcc422a, v24
	v_mul_f32_e32 v24, 0xbfb8aa3b, v24
	v_exp_f32_e32 v24, v24
	s_nop 0
	v_add_f32_e32 v24, 1.0, v24
	v_rcp_f32_e32 v133, v24
	s_nop 0
	v_pk_mul_f32 v[146:147], v[130:131], v[132:133]
	v_pk_mul_f32 v[130:131], v[112:113], v[140:141] op_sel_hi:[1,0]
	s_nop 0
	v_mul_f32_e32 v24, 0x3d372713, v130
	v_mul_f32_e32 v24, v130, v24
	v_fma_f32 v24, v130, v24, v130
	v_mul_f32_e32 v24, 0x3fcc422a, v24
	v_mul_f32_e32 v24, 0xbfb8aa3b, v24
	v_exp_f32_e32 v24, v24
	s_nop 0
	v_add_f32_e32 v24, 1.0, v24
	v_rcp_f32_e32 v132, v24
	v_mul_f32_e32 v24, 0x3d372713, v131
	v_mul_f32_e32 v24, v131, v24
	v_fma_f32 v24, v131, v24, v131
	v_mul_f32_e32 v24, 0x3fcc422a, v24
	v_mul_f32_e32 v24, 0xbfb8aa3b, v24
	v_exp_f32_e32 v24, v24
	s_nop 0
	v_add_f32_e32 v24, 1.0, v24
	v_rcp_f32_e32 v133, v24
	s_nop 0
	v_pk_mul_f32 v[148:149], v[130:131], v[132:133]
	v_pk_mul_f32 v[130:131], v[108:109], v[140:141] op_sel_hi:[1,0]
	s_nop 0
	v_mul_f32_e32 v24, 0x3d372713, v130
	v_mul_f32_e32 v24, v130, v24
	v_fma_f32 v24, v130, v24, v130
	v_mul_f32_e32 v24, 0x3fcc422a, v24
	v_mul_f32_e32 v24, 0xbfb8aa3b, v24
	v_exp_f32_e32 v24, v24
	s_nop 0
	v_add_f32_e32 v24, 1.0, v24
	v_rcp_f32_e32 v132, v24
	v_mul_f32_e32 v24, 0x3d372713, v131
	v_mul_f32_e32 v24, v131, v24
	v_fma_f32 v24, v131, v24, v131
	v_mul_f32_e32 v24, 0x3fcc422a, v24
	v_mul_f32_e32 v24, 0xbfb8aa3b, v24
	v_exp_f32_e32 v24, v24
	s_nop 0
	v_add_f32_e32 v24, 1.0, v24
	v_rcp_f32_e32 v133, v24
	s_nop 0
	v_pk_mul_f32 v[150:151], v[130:131], v[132:133]
	v_cvt_pk_bf16_f32 v130, v144, v145
	v_cvt_pk_bf16_f32 v131, v148, v149
	v_cvt_pk_bf16_f32 v132, v146, v147
	v_cvt_pk_bf16_f32 v133, v150, v151
	s_cbranch_vccnz .LBB0_416
	v_ashrrev_i32_e32 v175, 31, v174
	v_lshl_add_u64 v[154:155], v[174:175], 1, v[138:139]
	s_mov_b64 s[22:23], 0
	global_store_dwordx4 v[154:155], v[130:133], off

; DI float geluf_(float x) { return x * sigmoidf_(1.5957691216f * (x + 0.044715f * x * x * x)); }
; DI u32x4 pack8(const float* f) { u32x4 w; w.x = pk2(f[0], f[1]); w.y = pk2(f[2], f[3]); w.z = pk2(f[4], f[5]); w.w = pk2(f[6], f[7]); return w; }
; DI float rs_of(float ss, float inv_n) { return __builtin_amdgcn_rsqf(ss * inv_n + EPS); }
; DI float sum16_fq(const float* p, int fq) { const f32x4 a = *(const f32x4*)(p + 4 * fq); float s = (a[0] + a[1]) + (a[2] + a[3]); s += __shfl_xor(s, 16); s += __shfl_xor(s, 32); return s; }
; DI void epilogue(int kind, int l, const f32x4 (&acc)[2][2][4][2], const Unit& u, int wr, int wc, int fr, int fq) {
;     ...
;             for (int m = 0; m < 4; ++m) { const int row = row0 + ai * HALF + m * 16; const float rs = rs_of(sum16_fq(E.ss_in + (size_t)row * 16, fq), 1.f / 1024.f); float s1 = 0.f, s2 = 0.f;
; #pragma unroll
;                 for (int bj = 0; bj < 2; ++bj) { const int col = col0 + bj * HALF; float v[8];
; #pragma unroll
;                     for (int j = 0; j < 4; ++j) { v[j] = geluf_(acc[ai][bj][m][0][j] * rs); v[4 + j] = geluf_(acc[ai][bj][m][1][j] * rs); }
;                     const u32x4 w = pack8(v);
;                     if (isv) { *(u32x4*)(E.o1 + (size_t)row * DM + col - 1024) = w;
; #pragma unroll
;                         for (int j = 0; j < 8; ++j) { s1 += v[j]; s2 += v[j] * v[j]; } }
;                     else *(u32x4*)(E.o0 + (size_t)row * DM + col) = w; }
.LBB0_427:
	v_or_b32_e32 v136, 32, v172
	v_ashrrev_i32_e32 v137, 31, v136
	v_lshlrev_b64 v[130:131], 6, v[136:137]
	v_lshl_add_u64 v[130:131], v[134:135], 0, v[130:131]
	s_waitcnt lgkmcnt(0)
	v_mov_b32_e32 v130, v224
	v_mov_b32_e32 v131, v225
	v_mov_b32_e32 v132, v226
	v_mov_b32_e32 v133, v227
	v_lshlrev_b64 v[142:143], 11, v[136:137]
	s_mov_b64 s[22:23], -1
	s_and_b64 vcc, exec, s[42:43]
	v_mov_b32_e32 v138, v131
	v_mov_b32_e32 v139, v132
	v_mov_b32_e32 v131, v133
	v_pk_add_f32 v[130:131], v[138:139], v[130:131]
	v_lshl_add_u64 v[138:139], s[78:79], 0, v[142:143]
	v_add_f32_e32 v24, v130, v131
	ds_bpermute_b32 v130, v153, v24
	s_waitcnt lgkmcnt(0)
	v_add_f32_e32 v24, v24, v130
	ds_bpermute_b32 v130, v152, v24
	s_waitcnt lgkmcnt(0)
	v_add_f32_e32 v24, v24, v130
	v_fmamk_f32 v24, v24, 0x3a800000, v185
	v_rsq_f32_e32 v140, v24
	s_nop 0
	v_pk_mul_f32 v[130:131], v[94:95], v[140:141] op_sel_hi:[1,0]
	s_nop 0
	v_mul_f32_e32 v24, 0x3d372713, v130
	v_mul_f32_e32 v24, v130, v24
	v_fma_f32 v24, v130, v24, v130
	v_mul_f32_e32 v24, 0x3fcc422a, v24
	v_mul_f32_e32 v24, 0xbfb8aa3b, v24
	v_exp_f32_e32 v24, v24
	s_nop 0
	v_add_f32_e32 v24, 1.0, v24
	v_rcp_f32_e32 v132, v24
	v_mul_f32_e32 v24, 0x3d372713, v131
	v_mul_f32_e32 v24, v131, v24
	v_fma_f32 v24, v131, v24, v131
	v_mul_f32_e32 v24, 0x3fcc422a, v24
	v_mul_f32_e32 v24, 0xbfb8aa3b, v24
	v_exp_f32_e32 v24, v24
	s_nop 0
	v_add_f32_e32 v24, 1.0, v24
	v_rcp_f32_e32 v133, v24
	s_nop 0
	v_pk_mul_f32 v[144:145], v[130:131], v[132:133]
	v_pk_mul_f32 v[130:131], v[90:91], v[140:141] op_sel_hi:[1,0]
	s_nop 0
	v_mul_f32_e32 v24, 0x3d372713, v130
	v_mul_f32_e32 v24, v130, v24
	v_fma_f32 v24, v130, v24, v130
	v_mul_f32_e32 v24, 0x3fcc422a, v24
	v_mul_f32_e32 v24, 0xbfb8aa3b, v24
	v_exp_f32_e32 v24, v24
	s_nop 0
	v_add_f32_e32 v24, 1.0, v24
	v_rcp_f32_e32 v132, v24
	v_mul_f32_e32 v24, 0x3d372713, v131
	v_mul_f32_e32 v24, v131, v24
	v_fma_f32 v24, v131, v24, v131
	v_mul_f32_e32 v24, 0x3fcc422a, v24
	v_mul_f32_e32 v24, 0xbfb8aa3b, v24
	v_exp_f32_e32 v24, v24
	s_nop 0
	v_add_f32_e32 v24, 1.0, v24
	v_rcp_f32_e32 v133, v24
	s_nop 0
	v_pk_mul_f32 v[146:147], v[130:131], v[132:133]
	v_pk_mul_f32 v[130:131], v[96:97], v[140:141] op_sel_hi:[1,0]
	s_nop 0
	v_mul_f32_e32 v24, 0x3d372713, v130
	v_mul_f32_e32 v24, v130, v24
	v_fma_f32 v24, v130, v24, v130
	v_mul_f32_e32 v24, 0x3fcc422a, v24
	v_mul_f32_e32 v24, 0xbfb8aa3b, v24
	v_exp_f32_e32 v24, v24
	s_nop 0
	v_add_f32_e32 v24, 1.0, v24
	v_rcp_f32_e32 v132, v24
	v_mul_f32_e32 v24, 0x3d372713, v131
	v_mul_f32_e32 v24, v131, v24
	v_fma_f32 v24, v131, v24, v131
	v_mul_f32_e32 v24, 0x3fcc422a, v24
	v_mul_f32_e32 v24, 0xbfb8aa3b, v24
	v_exp_f32_e32 v24, v24
	s_nop 0
	v_add_f32_e32 v24, 1.0, v24
	v_rcp_f32_e32 v133, v24
	s_nop 0
	v_pk_mul_f32 v[148:149], v[130:131], v[132:133]
	v_pk_mul_f32 v[130:131], v[92:93], v[140:141] op_sel_hi:[1,0]
	s_nop 0
	v_mul_f32_e32 v24, 0x3d372713, v130
	v_mul_f32_e32 v24, v130, v24
	v_fma_f32 v24, v130, v24, v130
	v_mul_f32_e32 v24, 0x3fcc422a, v24
	v_mul_f32_e32 v24, 0xbfb8aa3b, v24
	v_exp_f32_e32 v24, v24
	s_nop 0
	v_add_f32_e32 v24, 1.0, v24
	v_rcp_f32_e32 v132, v24
	v_mul_f32_e32 v24, 0x3d372713, v131
	v_mul_f32_e32 v24, v131, v24
	v_fma_f32 v24, v131, v24, v131
	v_mul_f32_e32 v24, 0x3fcc422a, v24
	v_mul_f32_e32 v24, 0xbfb8aa3b, v24
	v_exp_f32_e32 v24, v24
	s_nop 0
	v_add_f32_e32 v24, 1.0, v24
	v_rcp_f32_e32 v133, v24
	s_nop 0
	v_pk_mul_f32 v[150:151], v[130:131], v[132:133]
	v_cvt_pk_bf16_f32 v130, v144, v145
	v_cvt_pk_bf16_f32 v131, v148, v149
	v_cvt_pk_bf16_f32 v132, v146, v147
	v_cvt_pk_bf16_f32 v133, v150, v151
	s_cbranch_vccnz .LBB0_429
	v_ashrrev_i32_e32 v175, 31, v174
	v_lshl_add_u64 v[154:155], v[174:175], 1, v[138:139]
	s_mov_b64 s[22:23], 0
	global_store_dwordx4 v[154:155], v[130:133], off

; DI float geluf_(float x) { return x * sigmoidf_(1.5957691216f * (x + 0.044715f * x * x * x)); }
; DI u32x4 pack8(const float* f) { u32x4 w; w.x = pk2(f[0], f[1]); w.y = pk2(f[2], f[3]); w.z = pk2(f[4], f[5]); w.w = pk2(f[6], f[7]); return w; }
; DI float rs_of(float ss, float inv_n) { return __builtin_amdgcn_rsqf(ss * inv_n + EPS); }
; DI float sum16_fq(const float* p, int fq) { const f32x4 a = *(const f32x4*)(p + 4 * fq); float s = (a[0] + a[1]) + (a[2] + a[3]); s += __shfl_xor(s, 16); s += __shfl_xor(s, 32); return s; }
; DI void epilogue(int kind, int l, const f32x4 (&acc)[2][2][4][2], const Unit& u, int wr, int wc, int fr, int fq) {
;     ...
;             for (int m = 0; m < 4; ++m) { const int row = row0 + ai * HALF + m * 16; const float rs = rs_of(sum16_fq(E.ss_in + (size_t)row * 16, fq), 1.f / 1024.f); float s1 = 0.f, s2 = 0.f;
; #pragma unroll
;                 for (int bj = 0; bj < 2; ++bj) { const int col = col0 + bj * HALF; float v[8];
; #pragma unroll
;                     for (int j = 0; j < 4; ++j) { v[j] = geluf_(acc[ai][bj][m][0][j] * rs); v[4 + j] = geluf_(acc[ai][bj][m][1][j] * rs); }
;                     const u32x4 w = pack8(v);
;                     if (isv) { *(u32x4*)(E.o1 + (size_t)row * DM + col - 1024) = w;
; #pragma unroll
;                         for (int j = 0; j < 8; ++j) { s1 += v[j]; s2 += v[j] * v[j]; } }
;                     else *(u32x4*)(E.o0 + (size_t)row * DM + col) = w; }
.LBB0_440:
	v_or_b32_e32 v136, 48, v172
	v_ashrrev_i32_e32 v137, 31, v136
	v_lshlrev_b64 v[130:131], 6, v[136:137]
	v_lshl_add_u64 v[130:131], v[134:135], 0, v[130:131]
	s_waitcnt lgkmcnt(0)
	v_mov_b32_e32 v130, v228
	v_mov_b32_e32 v131, v229
	v_mov_b32_e32 v132, v230
	v_mov_b32_e32 v133, v231
	v_lshlrev_b64 v[142:143], 11, v[136:137]
	s_mov_b64 s[22:23], -1
	s_and_b64 vcc, exec, s[42:43]
	v_mov_b32_e32 v138, v131
	v_mov_b32_e32 v139, v132
	v_mov_b32_e32 v131, v133
	v_pk_add_f32 v[130:131], v[138:139], v[130:131]
	v_lshl_add_u64 v[138:139], s[78:79], 0, v[142:143]
	v_add_f32_e32 v24, v130, v131
	ds_bpermute_b32 v130, v153, v24
	s_waitcnt lgkmcnt(0)
	v_add_f32_e32 v24, v24, v130
	ds_bpermute_b32 v130, v152, v24
	s_waitcnt lgkmcnt(0)
	v_add_f32_e32 v24, v24, v130
	v_fmamk_f32 v24, v24, 0x3a800000, v185
	v_rsq_f32_e32 v140, v24
	s_nop 0
	v_pk_mul_f32 v[130:131], v[78:79], v[140:141] op_sel_hi:[1,0]
	s_nop 0
	v_mul_f32_e32 v24, 0x3d372713, v130
	v_mul_f32_e32 v24, v130, v24
	v_fma_f32 v24, v130, v24, v130
	v_mul_f32_e32 v24, 0x3fcc422a, v24
	v_mul_f32_e32 v24, 0xbfb8aa3b, v24
	v_exp_f32_e32 v24, v24
	s_nop 0
	v_add_f32_e32 v24, 1.0, v24
	v_rcp_f32_e32 v132, v24
	v_mul_f32_e32 v24, 0x3d372713, v131
	v_mul_f32_e32 v24, v131, v24
	v_fma_f32 v24, v131, v24, v131
	v_mul_f32_e32 v24, 0x3fcc422a, v24
	v_mul_f32_e32 v24, 0xbfb8aa3b, v24
	v_exp_f32_e32 v24, v24
	s_nop 0
	v_add_f32_e32 v24, 1.0, v24
	v_rcp_f32_e32 v133, v24
	s_nop 0
	v_pk_mul_f32 v[144:145], v[130:131], v[132:133]
	v_pk_mul_f32 v[130:131], v[74:75], v[140:141] op_sel_hi:[1,0]
	s_nop 0
	v_mul_f32_e32 v24, 0x3d372713, v130
	v_mul_f32_e32 v24, v130, v24
	v_fma_f32 v24, v130, v24, v130
	v_mul_f32_e32 v24, 0x3fcc422a, v24
	v_mul_f32_e32 v24, 0xbfb8aa3b, v24
	v_exp_f32_e32 v24, v24
	s_nop 0
	v_add_f32_e32 v24, 1.0, v24
	v_rcp_f32_e32 v132, v24
	v_mul_f32_e32 v24, 0x3d372713, v131
	v_mul_f32_e32 v24, v131, v24
	v_fma_f32 v24, v131, v24, v131
	v_mul_f32_e32 v24, 0x3fcc422a, v24
	v_mul_f32_e32 v24, 0xbfb8aa3b, v24
	v_exp_f32_e32 v24, v24
	s_nop 0
	v_add_f32_e32 v24, 1.0, v24
	v_rcp_f32_e32 v133, v24
	s_nop 0
	v_pk_mul_f32 v[146:147], v[130:131], v[132:133]
	v_pk_mul_f32 v[130:131], v[80:81], v[140:141] op_sel_hi:[1,0]
	s_nop 0
	v_mul_f32_e32 v24, 0x3d372713, v130
	v_mul_f32_e32 v24, v130, v24
	v_fma_f32 v24, v130, v24, v130
	v_mul_f32_e32 v24, 0x3fcc422a, v24
	v_mul_f32_e32 v24, 0xbfb8aa3b, v24
	v_exp_f32_e32 v24, v24
	s_nop 0
	v_add_f32_e32 v24, 1.0, v24
	v_rcp_f32_e32 v132, v24
	v_mul_f32_e32 v24, 0x3d372713, v131
	v_mul_f32_e32 v24, v131, v24
	v_fma_f32 v24, v131, v24, v131
	v_mul_f32_e32 v24, 0x3fcc422a, v24
	v_mul_f32_e32 v24, 0xbfb8aa3b, v24
	v_exp_f32_e32 v24, v24
	s_nop 0
	v_add_f32_e32 v24, 1.0, v24
	v_rcp_f32_e32 v133, v24
	s_nop 0
	v_pk_mul_f32 v[148:149], v[130:131], v[132:133]
	v_pk_mul_f32 v[130:131], v[76:77], v[140:141] op_sel_hi:[1,0]
	s_nop 0
	v_mul_f32_e32 v24, 0x3d372713, v130
	v_mul_f32_e32 v24, v130, v24
	v_fma_f32 v24, v130, v24, v130
	v_mul_f32_e32 v24, 0x3fcc422a, v24
	v_mul_f32_e32 v24, 0xbfb8aa3b, v24
	v_exp_f32_e32 v24, v24
	s_nop 0
	v_add_f32_e32 v24, 1.0, v24
	v_rcp_f32_e32 v132, v24
	v_mul_f32_e32 v24, 0x3d372713, v131
	v_mul_f32_e32 v24, v131, v24
	v_fma_f32 v24, v131, v24, v131
	v_mul_f32_e32 v24, 0x3fcc422a, v24
	v_mul_f32_e32 v24, 0xbfb8aa3b, v24
	v_exp_f32_e32 v24, v24
	s_nop 0
	v_add_f32_e32 v24, 1.0, v24
	v_rcp_f32_e32 v133, v24
	s_nop 0
	v_pk_mul_f32 v[150:151], v[130:131], v[132:133]
	v_cvt_pk_bf16_f32 v130, v144, v145
	v_cvt_pk_bf16_f32 v131, v148, v149
	v_cvt_pk_bf16_f32 v132, v146, v147
	v_cvt_pk_bf16_f32 v133, v150, v151
	s_cbranch_vccnz .LBB0_442
	v_ashrrev_i32_e32 v175, 31, v174
	v_lshl_add_u64 v[154:155], v[174:175], 1, v[138:139]
	s_mov_b64 s[22:23], 0
	global_store_dwordx4 v[154:155], v[130:133], off

; DI float geluf_(float x) { return x * sigmoidf_(1.5957691216f * (x + 0.044715f * x * x * x)); }
; DI u32x4 pack8(const float* f) { u32x4 w; w.x = pk2(f[0], f[1]); w.y = pk2(f[2], f[3]); w.z = pk2(f[4], f[5]); w.w = pk2(f[6], f[7]); return w; }
; DI float rs_of(float ss, float inv_n) { return __builtin_amdgcn_rsqf(ss * inv_n + EPS); }
; DI float sum16_fq(const float* p, int fq) { const f32x4 a = *(const f32x4*)(p + 4 * fq); float s = (a[0] + a[1]) + (a[2] + a[3]); s += __shfl_xor(s, 16); s += __shfl_xor(s, 32); return s; }
; DI void epilogue(int kind, int l, const f32x4 (&acc)[2][2][4][2], const Unit& u, int wr, int wc, int fr, int fq) {
;     ...
;             for (int m = 0; m < 4; ++m) { const int row = row0 + ai * HALF + m * 16; const float rs = rs_of(sum16_fq(E.ss_in + (size_t)row * 16, fq), 1.f / 1024.f); float s1 = 0.f, s2 = 0.f;
; #pragma unroll
;                 for (int bj = 0; bj < 2; ++bj) { const int col = col0 + bj * HALF; float v[8];
; #pragma unroll
;                     for (int j = 0; j < 4; ++j) { v[j] = geluf_(acc[ai][bj][m][0][j] * rs); v[4 + j] = geluf_(acc[ai][bj][m][1][j] * rs); }
;                     const u32x4 w = pack8(v);
;                     if (isv) { *(u32x4*)(E.o1 + (size_t)row * DM + col - 1024) = w;
; #pragma unroll
;                         for (int j = 0; j < 8; ++j) { s1 += v[j]; s2 += v[j] * v[j]; } }
;                     else *(u32x4*)(E.o0 + (size_t)row * DM + col) = w; }
.LBB0_453:
	v_add_u32_e32 v136, 0x80, v172
	v_ashrrev_i32_e32 v137, 31, v136
	v_lshlrev_b64 v[130:131], 6, v[136:137]
	v_lshl_add_u64 v[130:131], v[134:135], 0, v[130:131]
	s_waitcnt lgkmcnt(0)
	v_mov_b32_e32 v130, v232
	v_mov_b32_e32 v131, v233
	v_mov_b32_e32 v132, v234
	v_mov_b32_e32 v133, v235
	v_lshlrev_b64 v[142:143], 11, v[136:137]
	s_mov_b64 s[22:23], -1
	s_and_b64 vcc, exec, s[42:43]
	v_mov_b32_e32 v138, v131
	v_mov_b32_e32 v139, v132
	v_mov_b32_e32 v131, v133
	v_pk_add_f32 v[130:131], v[138:139], v[130:131]
	v_lshl_add_u64 v[138:139], s[78:79], 0, v[142:143]
	v_add_f32_e32 v24, v130, v131
	ds_bpermute_b32 v130, v153, v24
	s_waitcnt lgkmcnt(0)
	v_add_f32_e32 v24, v24, v130
	ds_bpermute_b32 v130, v152, v24
	s_waitcnt lgkmcnt(0)
	v_add_f32_e32 v24, v24, v130
	v_fmamk_f32 v24, v24, 0x3a800000, v185
	v_rsq_f32_e32 v140, v24
	s_nop 0
	v_pk_mul_f32 v[130:131], v[62:63], v[140:141] op_sel_hi:[1,0]
	s_nop 0
	v_mul_f32_e32 v24, 0x3d372713, v130
	v_mul_f32_e32 v24, v130, v24
	v_fma_f32 v24, v130, v24, v130
	v_mul_f32_e32 v24, 0x3fcc422a, v24
	v_mul_f32_e32 v24, 0xbfb8aa3b, v24
	v_exp_f32_e32 v24, v24
	s_nop 0
	v_add_f32_e32 v24, 1.0, v24
	v_rcp_f32_e32 v132, v24
	v_mul_f32_e32 v24, 0x3d372713, v131
	v_mul_f32_e32 v24, v131, v24
	v_fma_f32 v24, v131, v24, v131
	v_mul_f32_e32 v24, 0x3fcc422a, v24
	v_mul_f32_e32 v24, 0xbfb8aa3b, v24
	v_exp_f32_e32 v24, v24
	s_nop 0
	v_add_f32_e32 v24, 1.0, v24
	v_rcp_f32_e32 v133, v24
	s_nop 0
	v_pk_mul_f32 v[144:145], v[130:131], v[132:133]
	v_pk_mul_f32 v[130:131], v[58:59], v[140:141] op_sel_hi:[1,0]
	s_nop 0
	v_mul_f32_e32 v24, 0x3d372713, v130
	v_mul_f32_e32 v24, v130, v24
	v_fma_f32 v24, v130, v24, v130
	v_mul_f32_e32 v24, 0x3fcc422a, v24
	v_mul_f32_e32 v24, 0xbfb8aa3b, v24
	v_exp_f32_e32 v24, v24
	s_nop 0
	v_add_f32_e32 v24, 1.0, v24
	v_rcp_f32_e32 v132, v24
	v_mul_f32_e32 v24, 0x3d372713, v131
	v_mul_f32_e32 v24, v131, v24
	v_fma_f32 v24, v131, v24, v131
	v_mul_f32_e32 v24, 0x3fcc422a, v24
	v_mul_f32_e32 v24, 0xbfb8aa3b, v24
	v_exp_f32_e32 v24, v24
	s_nop 0
	v_add_f32_e32 v24, 1.0, v24
	v_rcp_f32_e32 v133, v24
	s_nop 0
	v_pk_mul_f32 v[146:147], v[130:131], v[132:133]
	v_pk_mul_f32 v[130:131], v[64:65], v[140:141] op_sel_hi:[1,0]
	s_nop 0
	v_mul_f32_e32 v24, 0x3d372713, v130
	v_mul_f32_e32 v24, v130, v24
	v_fma_f32 v24, v130, v24, v130
	v_mul_f32_e32 v24, 0x3fcc422a, v24
	v_mul_f32_e32 v24, 0xbfb8aa3b, v24
	v_exp_f32_e32 v24, v24
	s_nop 0
	v_add_f32_e32 v24, 1.0, v24
	v_rcp_f32_e32 v132, v24
	v_mul_f32_e32 v24, 0x3d372713, v131
	v_mul_f32_e32 v24, v131, v24
	v_fma_f32 v24, v131, v24, v131
	v_mul_f32_e32 v24, 0x3fcc422a, v24
	v_mul_f32_e32 v24, 0xbfb8aa3b, v24
	v_exp_f32_e32 v24, v24
	s_nop 0
	v_add_f32_e32 v24, 1.0, v24
	v_rcp_f32_e32 v133, v24
	s_nop 0
	v_pk_mul_f32 v[148:149], v[130:131], v[132:133]
	v_pk_mul_f32 v[130:131], v[60:61], v[140:141] op_sel_hi:[1,0]
	s_nop 0
	v_mul_f32_e32 v24, 0x3d372713, v130
	v_mul_f32_e32 v24, v130, v24
	v_fma_f32 v24, v130, v24, v130
	v_mul_f32_e32 v24, 0x3fcc422a, v24
	v_mul_f32_e32 v24, 0xbfb8aa3b, v24
	v_exp_f32_e32 v24, v24
	s_nop 0
	v_add_f32_e32 v24, 1.0, v24
	v_rcp_f32_e32 v132, v24
	v_mul_f32_e32 v24, 0x3d372713, v131
	v_mul_f32_e32 v24, v131, v24
	v_fma_f32 v24, v131, v24, v131
	v_mul_f32_e32 v24, 0x3fcc422a, v24
	v_mul_f32_e32 v24, 0xbfb8aa3b, v24
	v_exp_f32_e32 v24, v24
	s_nop 0
	v_add_f32_e32 v24, 1.0, v24
	v_rcp_f32_e32 v133, v24
	s_nop 0
	v_pk_mul_f32 v[150:151], v[130:131], v[132:133]
	v_cvt_pk_bf16_f32 v130, v144, v145
	v_cvt_pk_bf16_f32 v131, v148, v149
	v_cvt_pk_bf16_f32 v132, v146, v147
	v_cvt_pk_bf16_f32 v133, v150, v151
	s_cbranch_vccnz .LBB0_455
	v_ashrrev_i32_e32 v175, 31, v174
	v_lshl_add_u64 v[154:155], v[174:175], 1, v[138:139]
	s_mov_b64 s[22:23], 0
	global_store_dwordx4 v[154:155], v[130:133], off

; DI float geluf_(float x) { return x * sigmoidf_(1.5957691216f * (x + 0.044715f * x * x * x)); }
; DI u32x4 pack8(const float* f) { u32x4 w; w.x = pk2(f[0], f[1]); w.y = pk2(f[2], f[3]); w.z = pk2(f[4], f[5]); w.w = pk2(f[6], f[7]); return w; }
; DI float rs_of(float ss, float inv_n) { return __builtin_amdgcn_rsqf(ss * inv_n + EPS); }
; DI float sum16_fq(const float* p, int fq) { const f32x4 a = *(const f32x4*)(p + 4 * fq); float s = (a[0] + a[1]) + (a[2] + a[3]); s += __shfl_xor(s, 16); s += __shfl_xor(s, 32); return s; }
; DI void epilogue(int kind, int l, const f32x4 (&acc)[2][2][4][2], const Unit& u, int wr, int wc, int fr, int fq) {
;     ...
;             for (int m = 0; m < 4; ++m) { const int row = row0 + ai * HALF + m * 16; const float rs = rs_of(sum16_fq(E.ss_in + (size_t)row * 16, fq), 1.f / 1024.f); float s1 = 0.f, s2 = 0.f;
; #pragma unroll
;                 for (int bj = 0; bj < 2; ++bj) { const int col = col0 + bj * HALF; float v[8];
; #pragma unroll
;                     for (int j = 0; j < 4; ++j) { v[j] = geluf_(acc[ai][bj][m][0][j] * rs); v[4 + j] = geluf_(acc[ai][bj][m][1][j] * rs); }
;                     const u32x4 w = pack8(v);
;                     if (isv) { *(u32x4*)(E.o1 + (size_t)row * DM + col - 1024) = w;
; #pragma unroll
;                         for (int j = 0; j < 8; ++j) { s1 += v[j]; s2 += v[j] * v[j]; } }
;                     else *(u32x4*)(E.o0 + (size_t)row * DM + col) = w; }
.LBB0_466:
	v_add_u32_e32 v136, 0x90, v172
	v_ashrrev_i32_e32 v137, 31, v136
	v_lshlrev_b64 v[130:131], 6, v[136:137]
	v_lshl_add_u64 v[130:131], v[134:135], 0, v[130:131]
	s_waitcnt lgkmcnt(0)
	v_mov_b32_e32 v130, v236
	v_mov_b32_e32 v131, v237
	v_mov_b32_e32 v132, v238
	v_mov_b32_e32 v133, v239
	v_lshlrev_b64 v[142:143], 11, v[136:137]
	s_mov_b64 s[22:23], -1
	s_and_b64 vcc, exec, s[42:43]
	v_mov_b32_e32 v138, v131
	v_mov_b32_e32 v139, v132
	v_mov_b32_e32 v131, v133
	v_pk_add_f32 v[130:131], v[138:139], v[130:131]
	v_lshl_add_u64 v[138:139], s[78:79], 0, v[142:143]
	v_add_f32_e32 v24, v130, v131
	ds_bpermute_b32 v130, v153, v24
	s_waitcnt lgkmcnt(0)
	v_add_f32_e32 v24, v24, v130
	ds_bpermute_b32 v130, v152, v24
	s_waitcnt lgkmcnt(0)
	v_add_f32_e32 v24, v24, v130
	v_fmamk_f32 v24, v24, 0x3a800000, v185
	v_rsq_f32_e32 v140, v24
	s_nop 0
	v_pk_mul_f32 v[130:131], v[46:47], v[140:141] op_sel_hi:[1,0]
	s_nop 0
	v_mul_f32_e32 v24, 0x3d372713, v130
	v_mul_f32_e32 v24, v130, v24
	v_fma_f32 v24, v130, v24, v130
	v_mul_f32_e32 v24, 0x3fcc422a, v24
	v_mul_f32_e32 v24, 0xbfb8aa3b, v24
	v_exp_f32_e32 v24, v24
	s_nop 0
	v_add_f32_e32 v24, 1.0, v24
	v_rcp_f32_e32 v132, v24
	v_mul_f32_e32 v24, 0x3d372713, v131
	v_mul_f32_e32 v24, v131, v24
	v_fma_f32 v24, v131, v24, v131
	v_mul_f32_e32 v24, 0x3fcc422a, v24
	v_mul_f32_e32 v24, 0xbfb8aa3b, v24
	v_exp_f32_e32 v24, v24
	s_nop 0
	v_add_f32_e32 v24, 1.0, v24
	v_rcp_f32_e32 v133, v24
	s_nop 0
	v_pk_mul_f32 v[144:145], v[130:131], v[132:133]
	v_pk_mul_f32 v[130:131], v[42:43], v[140:141] op_sel_hi:[1,0]
	s_nop 0
	v_mul_f32_e32 v24, 0x3d372713, v130
	v_mul_f32_e32 v24, v130, v24
	v_fma_f32 v24, v130, v24, v130
	v_mul_f32_e32 v24, 0x3fcc422a, v24
	v_mul_f32_e32 v24, 0xbfb8aa3b, v24
	v_exp_f32_e32 v24, v24
	s_nop 0
	v_add_f32_e32 v24, 1.0, v24
	v_rcp_f32_e32 v132, v24
	v_mul_f32_e32 v24, 0x3d372713, v131
	v_mul_f32_e32 v24, v131, v24
	v_fma_f32 v24, v131, v24, v131
	v_mul_f32_e32 v24, 0x3fcc422a, v24
	v_mul_f32_e32 v24, 0xbfb8aa3b, v24
	v_exp_f32_e32 v24, v24
	s_nop 0
	v_add_f32_e32 v24, 1.0, v24
	v_rcp_f32_e32 v133, v24
	s_nop 0
	v_pk_mul_f32 v[146:147], v[130:131], v[132:133]
	v_pk_mul_f32 v[130:131], v[48:49], v[140:141] op_sel_hi:[1,0]
	s_nop 0
	v_mul_f32_e32 v24, 0x3d372713, v130
	v_mul_f32_e32 v24, v130, v24
	v_fma_f32 v24, v130, v24, v130
	v_mul_f32_e32 v24, 0x3fcc422a, v24
	v_mul_f32_e32 v24, 0xbfb8aa3b, v24
	v_exp_f32_e32 v24, v24
	s_nop 0
	v_add_f32_e32 v24, 1.0, v24
	v_rcp_f32_e32 v132, v24
	v_mul_f32_e32 v24, 0x3d372713, v131
	v_mul_f32_e32 v24, v131, v24
	v_fma_f32 v24, v131, v24, v131
	v_mul_f32_e32 v24, 0x3fcc422a, v24
	v_mul_f32_e32 v24, 0xbfb8aa3b, v24
	v_exp_f32_e32 v24, v24
	s_nop 0
	v_add_f32_e32 v24, 1.0, v24
	v_rcp_f32_e32 v133, v24
	s_nop 0
	v_pk_mul_f32 v[148:149], v[130:131], v[132:133]
	v_pk_mul_f32 v[130:131], v[44:45], v[140:141] op_sel_hi:[1,0]
	s_nop 0
	v_mul_f32_e32 v24, 0x3d372713, v130
	v_mul_f32_e32 v24, v130, v24
	v_fma_f32 v24, v130, v24, v130
	v_mul_f32_e32 v24, 0x3fcc422a, v24
	v_mul_f32_e32 v24, 0xbfb8aa3b, v24
	v_exp_f32_e32 v24, v24
	s_nop 0
	v_add_f32_e32 v24, 1.0, v24
	v_rcp_f32_e32 v132, v24
	v_mul_f32_e32 v24, 0x3d372713, v131
	v_mul_f32_e32 v24, v131, v24
	v_fma_f32 v24, v131, v24, v131
	v_mul_f32_e32 v24, 0x3fcc422a, v24
	v_mul_f32_e32 v24, 0xbfb8aa3b, v24
	v_exp_f32_e32 v24, v24
	s_nop 0
	v_add_f32_e32 v24, 1.0, v24
	v_rcp_f32_e32 v133, v24
	s_nop 0
	v_pk_mul_f32 v[150:151], v[130:131], v[132:133]
	v_cvt_pk_bf16_f32 v130, v144, v145
	v_cvt_pk_bf16_f32 v131, v148, v149
	v_cvt_pk_bf16_f32 v132, v146, v147
	v_cvt_pk_bf16_f32 v133, v150, v151
	s_cbranch_vccnz .LBB0_468
	v_ashrrev_i32_e32 v175, 31, v174
	v_lshl_add_u64 v[154:155], v[174:175], 1, v[138:139]
	s_mov_b64 s[22:23], 0
	global_store_dwordx4 v[154:155], v[130:133], off

; DI float geluf_(float x) { return x * sigmoidf_(1.5957691216f * (x + 0.044715f * x * x * x)); }
; DI u32x4 pack8(const float* f) { u32x4 w; w.x = pk2(f[0], f[1]); w.y = pk2(f[2], f[3]); w.z = pk2(f[4], f[5]); w.w = pk2(f[6], f[7]); return w; }
; DI float rs_of(float ss, float inv_n) { return __builtin_amdgcn_rsqf(ss * inv_n + EPS); }
; DI float sum16_fq(const float* p, int fq) { const f32x4 a = *(const f32x4*)(p + 4 * fq); float s = (a[0] + a[1]) + (a[2] + a[3]); s += __shfl_xor(s, 16); s += __shfl_xor(s, 32); return s; }
; DI void epilogue(int kind, int l, const f32x4 (&acc)[2][2][4][2], const Unit& u, int wr, int wc, int fr, int fq) {
;     ...
;             for (int m = 0; m < 4; ++m) { const int row = row0 + ai * HALF + m * 16; const float rs = rs_of(sum16_fq(E.ss_in + (size_t)row * 16, fq), 1.f / 1024.f); float s1 = 0.f, s2 = 0.f;
; #pragma unroll
;                 for (int bj = 0; bj < 2; ++bj) { const int col = col0 + bj * HALF; float v[8];
; #pragma unroll
;                     for (int j = 0; j < 4; ++j) { v[j] = geluf_(acc[ai][bj][m][0][j] * rs); v[4 + j] = geluf_(acc[ai][bj][m][1][j] * rs); }
;                     const u32x4 w = pack8(v);
;                     if (isv) { *(u32x4*)(E.o1 + (size_t)row * DM + col - 1024) = w;
; #pragma unroll
;                         for (int j = 0; j < 8; ++j) { s1 += v[j]; s2 += v[j] * v[j]; } }
;                     else *(u32x4*)(E.o0 + (size_t)row * DM + col) = w; }
.LBB0_479:
	v_add_u32_e32 v136, 0xa0, v172
	v_ashrrev_i32_e32 v137, 31, v136
	v_lshlrev_b64 v[130:131], 6, v[136:137]
	v_lshl_add_u64 v[130:131], v[134:135], 0, v[130:131]
	s_waitcnt lgkmcnt(0)
	v_mov_b32_e32 v130, v240
	v_mov_b32_e32 v131, v241
	v_mov_b32_e32 v132, v242
	v_mov_b32_e32 v133, v243
	v_lshlrev_b64 v[142:143], 11, v[136:137]
	s_mov_b64 s[22:23], -1
	s_and_b64 vcc, exec, s[42:43]
	v_mov_b32_e32 v138, v131
	v_mov_b32_e32 v139, v132
	v_mov_b32_e32 v131, v133
	v_pk_add_f32 v[130:131], v[138:139], v[130:131]
	v_lshl_add_u64 v[138:139], s[78:79], 0, v[142:143]
	v_add_f32_e32 v24, v130, v131
	ds_bpermute_b32 v130, v153, v24
	s_waitcnt lgkmcnt(0)
	v_add_f32_e32 v24, v24, v130
	ds_bpermute_b32 v130, v152, v24
	s_waitcnt lgkmcnt(0)
	v_add_f32_e32 v24, v24, v130
	v_fmamk_f32 v24, v24, 0x3a800000, v185
	v_rsq_f32_e32 v140, v24
	s_nop 0
	v_pk_mul_f32 v[130:131], v[30:31], v[140:141] op_sel_hi:[1,0]
	s_nop 0
	v_mul_f32_e32 v24, 0x3d372713, v130
	v_mul_f32_e32 v24, v130, v24
	v_fma_f32 v24, v130, v24, v130
	v_mul_f32_e32 v24, 0x3fcc422a, v24
	v_mul_f32_e32 v24, 0xbfb8aa3b, v24
	v_exp_f32_e32 v24, v24
	s_nop 0
	v_add_f32_e32 v24, 1.0, v24
	v_rcp_f32_e32 v132, v24
	v_mul_f32_e32 v24, 0x3d372713, v131
	v_mul_f32_e32 v24, v131, v24
	v_fma_f32 v24, v131, v24, v131
	v_mul_f32_e32 v24, 0x3fcc422a, v24
	v_mul_f32_e32 v24, 0xbfb8aa3b, v24
	v_exp_f32_e32 v24, v24
	s_nop 0
	v_add_f32_e32 v24, 1.0, v24
	v_rcp_f32_e32 v133, v24
	s_nop 0
	v_pk_mul_f32 v[144:145], v[130:131], v[132:133]
	v_pk_mul_f32 v[130:131], v[26:27], v[140:141] op_sel_hi:[1,0]
	s_nop 0
	v_mul_f32_e32 v24, 0x3d372713, v130
	v_mul_f32_e32 v24, v130, v24
	v_fma_f32 v24, v130, v24, v130
	v_mul_f32_e32 v24, 0x3fcc422a, v24
	v_mul_f32_e32 v24, 0xbfb8aa3b, v24
	v_exp_f32_e32 v24, v24
	s_nop 0
	v_add_f32_e32 v24, 1.0, v24
	v_rcp_f32_e32 v132, v24
	v_mul_f32_e32 v24, 0x3d372713, v131
	v_mul_f32_e32 v24, v131, v24
	v_fma_f32 v24, v131, v24, v131
	v_mul_f32_e32 v24, 0x3fcc422a, v24
	v_mul_f32_e32 v24, 0xbfb8aa3b, v24
	v_exp_f32_e32 v24, v24
	s_nop 0
	v_add_f32_e32 v24, 1.0, v24
	v_rcp_f32_e32 v133, v24
	s_nop 0
	v_pk_mul_f32 v[146:147], v[130:131], v[132:133]
	v_pk_mul_f32 v[130:131], v[32:33], v[140:141] op_sel_hi:[1,0]
	s_nop 0
	v_mul_f32_e32 v24, 0x3d372713, v130
	v_mul_f32_e32 v24, v130, v24
	v_fma_f32 v24, v130, v24, v130
	v_mul_f32_e32 v24, 0x3fcc422a, v24
	v_mul_f32_e32 v24, 0xbfb8aa3b, v24
	v_exp_f32_e32 v24, v24
	s_nop 0
	v_add_f32_e32 v24, 1.0, v24
	v_rcp_f32_e32 v132, v24
	v_mul_f32_e32 v24, 0x3d372713, v131
	v_mul_f32_e32 v24, v131, v24
	v_fma_f32 v24, v131, v24, v131
	v_mul_f32_e32 v24, 0x3fcc422a, v24
	v_mul_f32_e32 v24, 0xbfb8aa3b, v24
	v_exp_f32_e32 v24, v24
	s_nop 0
	v_add_f32_e32 v24, 1.0, v24
	v_rcp_f32_e32 v133, v24
	s_nop 0
	v_pk_mul_f32 v[148:149], v[130:131], v[132:133]
	v_pk_mul_f32 v[130:131], v[28:29], v[140:141] op_sel_hi:[1,0]
	s_nop 0
	v_mul_f32_e32 v24, 0x3d372713, v130
	v_mul_f32_e32 v24, v130, v24
	v_fma_f32 v24, v130, v24, v130
	v_mul_f32_e32 v24, 0x3fcc422a, v24
	v_mul_f32_e32 v24, 0xbfb8aa3b, v24
	v_exp_f32_e32 v24, v24
	s_nop 0
	v_add_f32_e32 v24, 1.0, v24
	v_rcp_f32_e32 v132, v24
	v_mul_f32_e32 v24, 0x3d372713, v131
	v_mul_f32_e32 v24, v131, v24
	v_fma_f32 v24, v131, v24, v131
	v_mul_f32_e32 v24, 0x3fcc422a, v24
	v_mul_f32_e32 v24, 0xbfb8aa3b, v24
	v_exp_f32_e32 v24, v24
	s_nop 0
	v_add_f32_e32 v24, 1.0, v24
	v_rcp_f32_e32 v133, v24
	s_nop 0
	v_pk_mul_f32 v[150:151], v[130:131], v[132:133]
	v_cvt_pk_bf16_f32 v130, v144, v145
	v_cvt_pk_bf16_f32 v131, v148, v149
	v_cvt_pk_bf16_f32 v132, v146, v147
	v_cvt_pk_bf16_f32 v133, v150, v151
	s_cbranch_vccnz .LBB0_481
	v_ashrrev_i32_e32 v175, 31, v174
	v_lshl_add_u64 v[154:155], v[174:175], 1, v[138:139]
	s_mov_b64 s[22:23], 0
	global_store_dwordx4 v[154:155], v[130:133], off

; DI float geluf_(float x) { return x * sigmoidf_(1.5957691216f * (x + 0.044715f * x * x * x)); }
; DI u32x4 pack8(const float* f) { u32x4 w; w.x = pk2(f[0], f[1]); w.y = pk2(f[2], f[3]); w.z = pk2(f[4], f[5]); w.w = pk2(f[6], f[7]); return w; }
; DI float rs_of(float ss, float inv_n) { return __builtin_amdgcn_rsqf(ss * inv_n + EPS); }
; DI float sum16_fq(const float* p, int fq) { const f32x4 a = *(const f32x4*)(p + 4 * fq); float s = (a[0] + a[1]) + (a[2] + a[3]); s += __shfl_xor(s, 16); s += __shfl_xor(s, 32); return s; }
; DI void epilogue(int kind, int l, const f32x4 (&acc)[2][2][4][2], const Unit& u, int wr, int wc, int fr, int fq) {
;     ...
;             for (int m = 0; m < 4; ++m) { const int row = row0 + ai * HALF + m * 16; const float rs = rs_of(sum16_fq(E.ss_in + (size_t)row * 16, fq), 1.f / 1024.f); float s1 = 0.f, s2 = 0.f;
; #pragma unroll
;                 for (int bj = 0; bj < 2; ++bj) { const int col = col0 + bj * HALF; float v[8];
; #pragma unroll
;                     for (int j = 0; j < 4; ++j) { v[j] = geluf_(acc[ai][bj][m][0][j] * rs); v[4 + j] = geluf_(acc[ai][bj][m][1][j] * rs); }
;                     const u32x4 w = pack8(v);
;                     if (isv) { *(u32x4*)(E.o1 + (size_t)row * DM + col - 1024) = w;
; #pragma unroll
;                         for (int j = 0; j < 8; ++j) { s1 += v[j]; s2 += v[j] * v[j]; } }
;                     else *(u32x4*)(E.o0 + (size_t)row * DM + col) = w; }
.LBB0_492:
	v_add_u32_e32 v136, 0xb0, v172
	v_ashrrev_i32_e32 v137, 31, v136
	v_lshlrev_b64 v[130:131], 6, v[136:137]
	v_lshl_add_u64 v[130:131], v[134:135], 0, v[130:131]
	s_waitcnt lgkmcnt(0)
	v_mov_b32_e32 v130, v244
	v_mov_b32_e32 v131, v245
	v_mov_b32_e32 v132, v246
	v_mov_b32_e32 v133, v247
	v_lshlrev_b64 v[140:141], 11, v[136:137]
	s_mov_b64 s[22:23], -1
	s_and_b64 vcc, exec, s[42:43]
	v_mov_b32_e32 v134, v131
	v_mov_b32_e32 v135, v132
	v_mov_b32_e32 v131, v133
	v_pk_add_f32 v[130:131], v[134:135], v[130:131]
	v_lshl_add_u64 v[134:135], s[78:79], 0, v[140:141]
	v_add_f32_e32 v24, v130, v131
	ds_bpermute_b32 v130, v153, v24
	s_waitcnt lgkmcnt(0)
	v_add_f32_e32 v24, v24, v130
	ds_bpermute_b32 v130, v152, v24
	s_waitcnt lgkmcnt(0)
	v_add_f32_e32 v24, v24, v130
	v_fmamk_f32 v24, v24, 0x3a800000, v185
	v_rsq_f32_e32 v138, v24
	s_nop 0
	v_pk_mul_f32 v[130:131], v[12:13], v[138:139] op_sel_hi:[1,0]
	s_nop 0
	v_mul_f32_e32 v24, 0x3d372713, v130
	v_mul_f32_e32 v24, v130, v24
	v_fma_f32 v24, v130, v24, v130
	v_mul_f32_e32 v24, 0x3fcc422a, v24
	v_mul_f32_e32 v24, 0xbfb8aa3b, v24
	v_exp_f32_e32 v24, v24
	s_nop 0
	v_add_f32_e32 v24, 1.0, v24
	v_rcp_f32_e32 v132, v24
	v_mul_f32_e32 v24, 0x3d372713, v131
	v_mul_f32_e32 v24, v131, v24
	v_fma_f32 v24, v131, v24, v131
	v_mul_f32_e32 v24, 0x3fcc422a, v24
	v_mul_f32_e32 v24, 0xbfb8aa3b, v24
	v_exp_f32_e32 v24, v24
	s_nop 0
	v_add_f32_e32 v24, 1.0, v24
	v_rcp_f32_e32 v133, v24
	s_nop 0
	v_pk_mul_f32 v[142:143], v[130:131], v[132:133]
	v_pk_mul_f32 v[130:131], v[8:9], v[138:139] op_sel_hi:[1,0]
	s_nop 0
	v_mul_f32_e32 v24, 0x3d372713, v130
	v_mul_f32_e32 v24, v130, v24
	v_fma_f32 v24, v130, v24, v130
	v_mul_f32_e32 v24, 0x3fcc422a, v24
	v_mul_f32_e32 v24, 0xbfb8aa3b, v24
	v_exp_f32_e32 v24, v24
	s_nop 0
	v_add_f32_e32 v24, 1.0, v24
	v_rcp_f32_e32 v132, v24
	v_mul_f32_e32 v24, 0x3d372713, v131
	v_mul_f32_e32 v24, v131, v24
	v_fma_f32 v24, v131, v24, v131
	v_mul_f32_e32 v24, 0x3fcc422a, v24
	v_mul_f32_e32 v24, 0xbfb8aa3b, v24
	v_exp_f32_e32 v24, v24
	s_nop 0
	v_add_f32_e32 v24, 1.0, v24
	v_rcp_f32_e32 v133, v24
	s_nop 0
	v_pk_mul_f32 v[144:145], v[130:131], v[132:133]
	v_pk_mul_f32 v[130:131], v[14:15], v[138:139] op_sel_hi:[1,0]
	s_nop 0
	v_mul_f32_e32 v24, 0x3d372713, v130
	v_mul_f32_e32 v24, v130, v24
	v_fma_f32 v24, v130, v24, v130
	v_mul_f32_e32 v24, 0x3fcc422a, v24
	v_mul_f32_e32 v24, 0xbfb8aa3b, v24
	v_exp_f32_e32 v24, v24
	s_nop 0
	v_add_f32_e32 v24, 1.0, v24
	v_rcp_f32_e32 v132, v24
	v_mul_f32_e32 v24, 0x3d372713, v131
	v_mul_f32_e32 v24, v131, v24
	v_fma_f32 v24, v131, v24, v131
	v_mul_f32_e32 v24, 0x3fcc422a, v24
	v_mul_f32_e32 v24, 0xbfb8aa3b, v24
	v_exp_f32_e32 v24, v24
	s_nop 0
	v_add_f32_e32 v24, 1.0, v24
	v_rcp_f32_e32 v133, v24
	s_nop 0
	v_pk_mul_f32 v[146:147], v[130:131], v[132:133]
	v_pk_mul_f32 v[130:131], v[10:11], v[138:139] op_sel_hi:[1,0]
	s_nop 0
	v_mul_f32_e32 v24, 0x3d372713, v130
	v_mul_f32_e32 v24, v130, v24
	v_fma_f32 v24, v130, v24, v130
	v_mul_f32_e32 v24, 0x3fcc422a, v24
	v_mul_f32_e32 v24, 0xbfb8aa3b, v24
	v_exp_f32_e32 v24, v24
	s_nop 0
	v_add_f32_e32 v24, 1.0, v24
	v_rcp_f32_e32 v132, v24
	v_mul_f32_e32 v24, 0x3d372713, v131
	v_mul_f32_e32 v24, v131, v24
	v_fma_f32 v24, v131, v24, v131
	v_mul_f32_e32 v24, 0x3fcc422a, v24
	v_mul_f32_e32 v24, 0xbfb8aa3b, v24
	v_exp_f32_e32 v24, v24
	s_nop 0
	v_add_f32_e32 v24, 1.0, v24
	v_rcp_f32_e32 v133, v24
	s_nop 0
	v_pk_mul_f32 v[148:149], v[130:131], v[132:133]
	v_cvt_pk_bf16_f32 v130, v142, v143
	v_cvt_pk_bf16_f32 v131, v146, v147
	v_cvt_pk_bf16_f32 v132, v144, v145
	v_cvt_pk_bf16_f32 v133, v148, v149
	s_cbranch_vccnz .LBB0_494
	v_ashrrev_i32_e32 v175, 31, v174
	v_lshl_add_u64 v[150:151], v[174:175], 1, v[134:135]
	s_mov_b64 s[22:23], 0
	global_store_dwordx4 v[150:151], v[130:133], off

; DI unsigned pk2(float lo, float hi) { const f32x2v v = {lo, hi}; const bf16x2v b = __builtin_convertvector(v, bf16x2v); return __builtin_bit_cast(unsigned, b); }
; DI float rs_of(float ss, float inv_n) { return __builtin_amdgcn_rsqf(ss * inv_n + EPS); }
; DI float sum16_fq(const float* p, int fq) { const f32x4 a = *(const f32x4*)(p + 4 * fq); float s = (a[0] + a[1]) + (a[2] + a[3]); s += __shfl_xor(s, 16); s += __shfl_xor(s, 32); return s; }
; DI void epilogue(int kind, int l, const f32x4 (&acc)[2][2][4][2], const Unit& u, int wr, int wc, int fr, int fq) {
;     ...
;             for (int m = 0; m < 4; ++m) { const int row = row0 + ai * HALF + m * 16; const float rs = rs_of(sum16_fq(E.ss_in + (size_t)row * 16, fq), 1.f / 1024.f);
; #pragma unroll
;                 for (int bj = 0; bj < 2; ++bj) { const int col = col0 + bj * HALF; const f32x4 v0 = acc[ai][bj][m][0] * rs, v1 = acc[ai][bj][m][1] * rs;
;                     if (col < 5120) { u32x4 w; w.x = pk2(v0[0], v0[1]); w.y = pk2(v0[2], v0[3]); w.z = pk2(v1[0], v1[1]); w.w = pk2(v1[2], v1[3]);
;                         if (col < 2048) *(u32x4*)(E.o0 + (size_t)row * 2048 + col) = w; else *(u32x4*)(E.o1 + (size_t)row * 3072 + (col - 2048)) = w; }
;                     else if (col < 5152) { float* tp = E.f0 + (size_t)row * 32 + (col - 5120); *(f32x4*)tp = v0; *(f32x4*)(tp + 4) = v1; } } }
.LBB0_508:
	s_andn2_b64 vcc, exec, s[46:47]
	v_readlane_b32 s46, v255, 54
	v_readlane_b32 s47, v255, 55
	s_cbranch_vccnz .LBB0_662
	v_lshlrev_b32_e32 v24, 2, v166
	v_ashrrev_i32_e32 v173, 31, v172
	v_lshl_add_u64 v[138:139], s[88:89], 0, v[24:25]
	v_lshlrev_b64 v[130:131], 6, v[172:173]
	v_lshl_add_u64 v[130:131], v[138:139], 0, v[130:131]
	s_waitcnt lgkmcnt(0)
	global_load_dwordx4 v[216:219], v[130:131], off
	global_load_dwordx4 v[220:223], v[130:131], off offset:1024
	global_load_dwordx4 v[224:227], v[130:131], off offset:2048
	global_load_dwordx4 v[228:231], v[130:131], off offset:3072
	v_mov_b32_e32 v250, 0x2000
	v_mov_b32_e32 v251, 0
	v_lshl_add_u64 v[248:249], v[130:131], 0, v[250:251]
	global_load_dwordx4 v[232:235], v[248:249], off
	global_load_dwordx4 v[236:239], v[248:249], off offset:1024
	global_load_dwordx4 v[240:243], v[248:249], off offset:2048
	global_load_dwordx4 v[244:247], v[248:249], off offset:3072
	v_and_b32_e32 v134, 64, v187
	v_xor_b32_e32 v24, 16, v187
	v_add_u32_e32 v136, 64, v134
	v_cmp_lt_i32_e32 vcc, v24, v136
	s_movk_i32 s18, 0x13ff
	v_cmp_lt_i32_e64 s[42:43], s18, v174
	v_cndmask_b32_e32 v24, v187, v24, vcc
	v_lshlrev_b32_e32 v148, 2, v24
	s_waitcnt vmcnt(0)
	v_mov_b32_e32 v130, v216
	v_mov_b32_e32 v131, v217
	v_mov_b32_e32 v132, v218
	v_mov_b32_e32 v133, v219
	v_mov_b32_e32 v134, v131
	v_mov_b32_e32 v135, v132
	v_mov_b32_e32 v131, v133
	v_pk_add_f32 v[130:131], v[134:135], v[130:131]
	s_nop 0
	v_add_f32_e32 v24, v130, v131
	ds_bpermute_b32 v130, v148, v24
	v_xor_b32_e32 v131, 32, v187
	v_cmp_lt_i32_e32 vcc, v131, v136
	s_waitcnt lgkmcnt(0)
	v_add_f32_e32 v24, v24, v130
	v_cndmask_b32_e32 v131, v187, v131, vcc
	v_lshlrev_b32_e32 v149, 2, v131
	ds_bpermute_b32 v130, v149, v24
	s_waitcnt lgkmcnt(0)
	v_add_f32_e32 v24, v24, v130
	v_fmamk_f32 v24, v24, 0x3a800000, v185
	v_rsq_f32_e32 v142, v24
	v_lshlrev_b64 v[130:131], 7, v[172:173]
	v_lshl_add_u64 v[140:141], s[16:17], 0, v[130:131]
	v_pk_mul_f32 v[132:133], v[128:129], v[142:143] op_sel_hi:[1,0]
	v_pk_mul_f32 v[130:131], v[126:127], v[142:143] op_sel_hi:[1,0]
	v_pk_mul_f32 v[136:137], v[124:125], v[142:143] op_sel_hi:[1,0]
	v_pk_mul_f32 v[134:135], v[122:123], v[142:143] op_sel_hi:[1,0]
	s_and_saveexec_b64 s[18:19], s[42:43]
	s_xor_b64 s[18:19], exec, s[18:19]
	s_cbranch_execz .LBB0_512
	s_cmpk_gt_u32 s93, 0x141f
	s_cbranch_scc1 .LBB0_512
	v_mov_b32_e32 v175, v25
	v_lshl_add_u64 v[144:145], v[174:175], 2, v[140:141]
	v_add_co_u32_e32 v146, vcc, 0xffffb000, v144
	s_nop 1
	v_addc_co_u32_e32 v147, vcc, -1, v145, vcc
	global_store_dwordx4 v[146:147], v[130:133], off
	s_nop 1
	v_add_co_u32_e32 v130, vcc, 0xffffc000, v144
	s_nop 1
	v_addc_co_u32_e32 v131, vcc, -1, v145, vcc
	global_store_dwordx4 v[130:131], v[134:137], off offset:-4080

; DI unsigned pk2(float lo, float hi) { const f32x2v v = {lo, hi}; const bf16x2v b = __builtin_convertvector(v, bf16x2v); return __builtin_bit_cast(unsigned, b); }
; DI float rs_of(float ss, float inv_n) { return __builtin_amdgcn_rsqf(ss * inv_n + EPS); }
; DI float sum16_fq(const float* p, int fq) { const f32x4 a = *(const f32x4*)(p + 4 * fq); float s = (a[0] + a[1]) + (a[2] + a[3]); s += __shfl_xor(s, 16); s += __shfl_xor(s, 32); return s; }
; DI void epilogue(int kind, int l, const f32x4 (&acc)[2][2][4][2], const Unit& u, int wr, int wc, int fr, int fq) {
;     ...
;             for (int m = 0; m < 4; ++m) { const int row = row0 + ai * HALF + m * 16; const float rs = rs_of(sum16_fq(E.ss_in + (size_t)row * 16, fq), 1.f / 1024.f);
; #pragma unroll
;                 for (int bj = 0; bj < 2; ++bj) { const int col = col0 + bj * HALF; const f32x4 v0 = acc[ai][bj][m][0] * rs, v1 = acc[ai][bj][m][1] * rs;
;                     if (col < 5120) { u32x4 w; w.x = pk2(v0[0], v0[1]); w.y = pk2(v0[2], v0[3]); w.z = pk2(v1[0], v1[1]); w.w = pk2(v1[2], v1[3]);
;                         if (col < 2048) *(u32x4*)(E.o0 + (size_t)row * 2048 + col) = w; else *(u32x4*)(E.o1 + (size_t)row * 3072 + (col - 2048)) = w; }
;                     else if (col < 5152) { float* tp = E.f0 + (size_t)row * 32 + (col - 5120); *(f32x4*)tp = v0; *(f32x4*)(tp + 4) = v1; } } }
.LBB0_528:
	s_or_b64 exec, exec, s[18:19]
	v_or_b32_e32 v144, 16, v172
	v_ashrrev_i32_e32 v145, 31, v144
	v_lshlrev_b64 v[130:131], 6, v[144:145]
	v_lshl_add_u64 v[130:131], v[138:139], 0, v[130:131]
	v_mov_b32_e32 v130, v220
	v_mov_b32_e32 v131, v221
	v_mov_b32_e32 v132, v222
	v_mov_b32_e32 v133, v223
	v_mov_b32_e32 v134, v131
	v_mov_b32_e32 v135, v132
	v_mov_b32_e32 v131, v133
	v_pk_add_f32 v[130:131], v[134:135], v[130:131]
	s_nop 0
	v_add_f32_e32 v130, v130, v131
	ds_bpermute_b32 v131, v148, v130
	s_waitcnt lgkmcnt(0)
	v_add_f32_e32 v130, v130, v131
	ds_bpermute_b32 v131, v149, v130
	s_waitcnt lgkmcnt(0)
	v_add_f32_e32 v130, v130, v131
	v_fmamk_f32 v130, v130, 0x3a800000, v185
	v_rsq_f32_e32 v142, v130
	v_lshlrev_b64 v[130:131], 7, v[144:145]
	v_lshl_add_u64 v[140:141], s[16:17], 0, v[130:131]
	v_pk_mul_f32 v[132:133], v[112:113], v[142:143] op_sel_hi:[1,0]
	v_pk_mul_f32 v[130:131], v[110:111], v[142:143] op_sel_hi:[1,0]
	v_pk_mul_f32 v[136:137], v[108:109], v[142:143] op_sel_hi:[1,0]
	v_pk_mul_f32 v[134:135], v[106:107], v[142:143] op_sel_hi:[1,0]
	s_and_saveexec_b64 s[18:19], s[42:43]
	s_xor_b64 s[18:19], exec, s[18:19]
	s_cbranch_execz .LBB0_531
	s_cmpk_gt_u32 s93, 0x141f
	s_cbranch_scc1 .LBB0_531
	v_mov_b32_e32 v175, v25
	v_lshl_add_u64 v[146:147], v[174:175], 2, v[140:141]
	v_add_co_u32_e32 v150, vcc, 0xffffb000, v146
	s_nop 1
	v_addc_co_u32_e32 v151, vcc, -1, v147, vcc
	global_store_dwordx4 v[150:151], v[130:133], off
	s_nop 1
	v_add_co_u32_e32 v130, vcc, 0xffffc000, v146
	s_nop 1
	v_addc_co_u32_e32 v131, vcc, -1, v147, vcc
	global_store_dwordx4 v[130:131], v[134:137], off offset:-4080

; DI unsigned pk2(float lo, float hi) { const f32x2v v = {lo, hi}; const bf16x2v b = __builtin_convertvector(v, bf16x2v); return __builtin_bit_cast(unsigned, b); }
; DI float rs_of(float ss, float inv_n) { return __builtin_amdgcn_rsqf(ss * inv_n + EPS); }
; DI float sum16_fq(const float* p, int fq) { const f32x4 a = *(const f32x4*)(p + 4 * fq); float s = (a[0] + a[1]) + (a[2] + a[3]); s += __shfl_xor(s, 16); s += __shfl_xor(s, 32); return s; }
; DI void epilogue(int kind, int l, const f32x4 (&acc)[2][2][4][2], const Unit& u, int wr, int wc, int fr, int fq) {
;     ...
;             for (int m = 0; m < 4; ++m) { const int row = row0 + ai * HALF + m * 16; const float rs = rs_of(sum16_fq(E.ss_in + (size_t)row * 16, fq), 1.f / 1024.f);
; #pragma unroll
;                 for (int bj = 0; bj < 2; ++bj) { const int col = col0 + bj * HALF; const f32x4 v0 = acc[ai][bj][m][0] * rs, v1 = acc[ai][bj][m][1] * rs;
;                     if (col < 5120) { u32x4 w; w.x = pk2(v0[0], v0[1]); w.y = pk2(v0[2], v0[3]); w.z = pk2(v1[0], v1[1]); w.w = pk2(v1[2], v1[3]);
;                         if (col < 2048) *(u32x4*)(E.o0 + (size_t)row * 2048 + col) = w; else *(u32x4*)(E.o1 + (size_t)row * 3072 + (col - 2048)) = w; }
;                     else if (col < 5152) { float* tp = E.f0 + (size_t)row * 32 + (col - 5120); *(f32x4*)tp = v0; *(f32x4*)(tp + 4) = v1; } } }
.LBB0_547:
	s_or_b64 exec, exec, s[18:19]
	v_or_b32_e32 v144, 32, v172
	v_ashrrev_i32_e32 v145, 31, v144
	v_lshlrev_b64 v[130:131], 6, v[144:145]
	v_lshl_add_u64 v[130:131], v[138:139], 0, v[130:131]
	v_mov_b32_e32 v130, v224
	v_mov_b32_e32 v131, v225
	v_mov_b32_e32 v132, v226
	v_mov_b32_e32 v133, v227
	v_mov_b32_e32 v134, v131
	v_mov_b32_e32 v135, v132
	v_mov_b32_e32 v131, v133
	v_pk_add_f32 v[130:131], v[134:135], v[130:131]
	s_nop 0
	v_add_f32_e32 v130, v130, v131
	ds_bpermute_b32 v131, v148, v130
	s_waitcnt lgkmcnt(0)
	v_add_f32_e32 v130, v130, v131
	ds_bpermute_b32 v131, v149, v130
	s_waitcnt lgkmcnt(0)
	v_add_f32_e32 v130, v130, v131
	v_fmamk_f32 v130, v130, 0x3a800000, v185
	v_rsq_f32_e32 v142, v130
	v_lshlrev_b64 v[130:131], 7, v[144:145]
	v_lshl_add_u64 v[140:141], s[16:17], 0, v[130:131]
	v_pk_mul_f32 v[132:133], v[96:97], v[142:143] op_sel_hi:[1,0]
	v_pk_mul_f32 v[130:131], v[94:95], v[142:143] op_sel_hi:[1,0]
	v_pk_mul_f32 v[136:137], v[92:93], v[142:143] op_sel_hi:[1,0]
	v_pk_mul_f32 v[134:135], v[90:91], v[142:143] op_sel_hi:[1,0]
	s_and_saveexec_b64 s[18:19], s[42:43]
	s_xor_b64 s[18:19], exec, s[18:19]
	s_cbranch_execz .LBB0_550
	s_cmpk_gt_u32 s93, 0x141f
	s_cbranch_scc1 .LBB0_550
	v_mov_b32_e32 v175, v25
	v_lshl_add_u64 v[146:147], v[174:175], 2, v[140:141]
	v_add_co_u32_e32 v150, vcc, 0xffffb000, v146
	s_nop 1
	v_addc_co_u32_e32 v151, vcc, -1, v147, vcc
	global_store_dwordx4 v[150:151], v[130:133], off
	s_nop 1
	v_add_co_u32_e32 v130, vcc, 0xffffc000, v146
	s_nop 1
	v_addc_co_u32_e32 v131, vcc, -1, v147, vcc
	global_store_dwordx4 v[130:131], v[134:137], off offset:-4080

; DI unsigned pk2(float lo, float hi) { const f32x2v v = {lo, hi}; const bf16x2v b = __builtin_convertvector(v, bf16x2v); return __builtin_bit_cast(unsigned, b); }
; DI float rs_of(float ss, float inv_n) { return __builtin_amdgcn_rsqf(ss * inv_n + EPS); }
; DI float sum16_fq(const float* p, int fq) { const f32x4 a = *(const f32x4*)(p + 4 * fq); float s = (a[0] + a[1]) + (a[2] + a[3]); s += __shfl_xor(s, 16); s += __shfl_xor(s, 32); return s; }
; DI void epilogue(int kind, int l, const f32x4 (&acc)[2][2][4][2], const Unit& u, int wr, int wc, int fr, int fq) {
;     ...
;             for (int m = 0; m < 4; ++m) { const int row = row0 + ai * HALF + m * 16; const float rs = rs_of(sum16_fq(E.ss_in + (size_t)row * 16, fq), 1.f / 1024.f);
; #pragma unroll
;                 for (int bj = 0; bj < 2; ++bj) { const int col = col0 + bj * HALF; const f32x4 v0 = acc[ai][bj][m][0] * rs, v1 = acc[ai][bj][m][1] * rs;
;                     if (col < 5120) { u32x4 w; w.x = pk2(v0[0], v0[1]); w.y = pk2(v0[2], v0[3]); w.z = pk2(v1[0], v1[1]); w.w = pk2(v1[2], v1[3]);
;                         if (col < 2048) *(u32x4*)(E.o0 + (size_t)row * 2048 + col) = w; else *(u32x4*)(E.o1 + (size_t)row * 3072 + (col - 2048)) = w; }
;                     else if (col < 5152) { float* tp = E.f0 + (size_t)row * 32 + (col - 5120); *(f32x4*)tp = v0; *(f32x4*)(tp + 4) = v1; } } }
.LBB0_566:
	s_or_b64 exec, exec, s[18:19]
	v_or_b32_e32 v144, 48, v172
	v_ashrrev_i32_e32 v145, 31, v144
	v_lshlrev_b64 v[130:131], 6, v[144:145]
	v_lshl_add_u64 v[130:131], v[138:139], 0, v[130:131]
	v_mov_b32_e32 v130, v228
	v_mov_b32_e32 v131, v229
	v_mov_b32_e32 v132, v230
	v_mov_b32_e32 v133, v231
	v_mov_b32_e32 v134, v131
	v_mov_b32_e32 v135, v132
	v_mov_b32_e32 v131, v133
	v_pk_add_f32 v[130:131], v[134:135], v[130:131]
	s_nop 0
	v_add_f32_e32 v130, v130, v131
	ds_bpermute_b32 v131, v148, v130
	s_waitcnt lgkmcnt(0)
	v_add_f32_e32 v130, v130, v131
	ds_bpermute_b32 v131, v149, v130
	s_waitcnt lgkmcnt(0)
	v_add_f32_e32 v130, v130, v131
	v_fmamk_f32 v130, v130, 0x3a800000, v185
	v_rsq_f32_e32 v142, v130
	v_lshlrev_b64 v[130:131], 7, v[144:145]
	v_lshl_add_u64 v[140:141], s[16:17], 0, v[130:131]
	v_pk_mul_f32 v[132:133], v[80:81], v[142:143] op_sel_hi:[1,0]
	v_pk_mul_f32 v[130:131], v[78:79], v[142:143] op_sel_hi:[1,0]
	v_pk_mul_f32 v[136:137], v[76:77], v[142:143] op_sel_hi:[1,0]
	v_pk_mul_f32 v[134:135], v[74:75], v[142:143] op_sel_hi:[1,0]
	s_and_saveexec_b64 s[18:19], s[42:43]
	s_xor_b64 s[18:19], exec, s[18:19]
	s_cbranch_execz .LBB0_569
	s_cmpk_gt_u32 s93, 0x141f
	s_cbranch_scc1 .LBB0_569
	v_mov_b32_e32 v175, v25
	v_lshl_add_u64 v[146:147], v[174:175], 2, v[140:141]
	v_add_co_u32_e32 v150, vcc, 0xffffb000, v146
	s_nop 1
	v_addc_co_u32_e32 v151, vcc, -1, v147, vcc
	global_store_dwordx4 v[150:151], v[130:133], off
	s_nop 1
	v_add_co_u32_e32 v130, vcc, 0xffffc000, v146
	s_nop 1
	v_addc_co_u32_e32 v131, vcc, -1, v147, vcc
	global_store_dwordx4 v[130:131], v[134:137], off offset:-4080

; DI unsigned pk2(float lo, float hi) { const f32x2v v = {lo, hi}; const bf16x2v b = __builtin_convertvector(v, bf16x2v); return __builtin_bit_cast(unsigned, b); }
; DI float rs_of(float ss, float inv_n) { return __builtin_amdgcn_rsqf(ss * inv_n + EPS); }
; DI float sum16_fq(const float* p, int fq) { const f32x4 a = *(const f32x4*)(p + 4 * fq); float s = (a[0] + a[1]) + (a[2] + a[3]); s += __shfl_xor(s, 16); s += __shfl_xor(s, 32); return s; }
; DI void epilogue(int kind, int l, const f32x4 (&acc)[2][2][4][2], const Unit& u, int wr, int wc, int fr, int fq) {
;     ...
;             for (int m = 0; m < 4; ++m) { const int row = row0 + ai * HALF + m * 16; const float rs = rs_of(sum16_fq(E.ss_in + (size_t)row * 16, fq), 1.f / 1024.f);
; #pragma unroll
;                 for (int bj = 0; bj < 2; ++bj) { const int col = col0 + bj * HALF; const f32x4 v0 = acc[ai][bj][m][0] * rs, v1 = acc[ai][bj][m][1] * rs;
;                     if (col < 5120) { u32x4 w; w.x = pk2(v0[0], v0[1]); w.y = pk2(v0[2], v0[3]); w.z = pk2(v1[0], v1[1]); w.w = pk2(v1[2], v1[3]);
;                         if (col < 2048) *(u32x4*)(E.o0 + (size_t)row * 2048 + col) = w; else *(u32x4*)(E.o1 + (size_t)row * 3072 + (col - 2048)) = w; }
;                     else if (col < 5152) { float* tp = E.f0 + (size_t)row * 32 + (col - 5120); *(f32x4*)tp = v0; *(f32x4*)(tp + 4) = v1; } } }
.LBB0_585:
	s_or_b64 exec, exec, s[18:19]
	v_add_u32_e32 v144, 0x80, v172
	v_ashrrev_i32_e32 v145, 31, v144
	v_lshlrev_b64 v[130:131], 6, v[144:145]
	v_lshl_add_u64 v[130:131], v[138:139], 0, v[130:131]
	v_mov_b32_e32 v130, v232
	v_mov_b32_e32 v131, v233
	v_mov_b32_e32 v132, v234
	v_mov_b32_e32 v133, v235
	v_mov_b32_e32 v134, v131
	v_mov_b32_e32 v135, v132
	v_mov_b32_e32 v131, v133
	v_pk_add_f32 v[130:131], v[134:135], v[130:131]
	s_nop 0
	v_add_f32_e32 v130, v130, v131
	ds_bpermute_b32 v131, v148, v130
	s_waitcnt lgkmcnt(0)
	v_add_f32_e32 v130, v130, v131
	ds_bpermute_b32 v131, v149, v130
	s_waitcnt lgkmcnt(0)
	v_add_f32_e32 v130, v130, v131
	v_fmamk_f32 v130, v130, 0x3a800000, v185
	v_rsq_f32_e32 v142, v130
	v_lshlrev_b64 v[130:131], 7, v[144:145]
	v_lshl_add_u64 v[140:141], s[16:17], 0, v[130:131]
	v_pk_mul_f32 v[132:133], v[64:65], v[142:143] op_sel_hi:[1,0]
	v_pk_mul_f32 v[130:131], v[62:63], v[142:143] op_sel_hi:[1,0]
	v_pk_mul_f32 v[136:137], v[60:61], v[142:143] op_sel_hi:[1,0]
	v_pk_mul_f32 v[134:135], v[58:59], v[142:143] op_sel_hi:[1,0]
	s_and_saveexec_b64 s[18:19], s[42:43]
	s_xor_b64 s[18:19], exec, s[18:19]
	s_cbranch_execz .LBB0_588
	s_cmpk_gt_u32 s93, 0x141f
	s_cbranch_scc1 .LBB0_588
	v_mov_b32_e32 v175, v25
	v_lshl_add_u64 v[146:147], v[174:175], 2, v[140:141]
	v_add_co_u32_e32 v150, vcc, 0xffffb000, v146
	s_nop 1
	v_addc_co_u32_e32 v151, vcc, -1, v147, vcc
	global_store_dwordx4 v[150:151], v[130:133], off
	s_nop 1
	v_add_co_u32_e32 v130, vcc, 0xffffc000, v146
	s_nop 1
	v_addc_co_u32_e32 v131, vcc, -1, v147, vcc
	global_store_dwordx4 v[130:131], v[134:137], off offset:-4080

; DI unsigned pk2(float lo, float hi) { const f32x2v v = {lo, hi}; const bf16x2v b = __builtin_convertvector(v, bf16x2v); return __builtin_bit_cast(unsigned, b); }
; DI float rs_of(float ss, float inv_n) { return __builtin_amdgcn_rsqf(ss * inv_n + EPS); }
; DI float sum16_fq(const float* p, int fq) { const f32x4 a = *(const f32x4*)(p + 4 * fq); float s = (a[0] + a[1]) + (a[2] + a[3]); s += __shfl_xor(s, 16); s += __shfl_xor(s, 32); return s; }
; DI void epilogue(int kind, int l, const f32x4 (&acc)[2][2][4][2], const Unit& u, int wr, int wc, int fr, int fq) {
;     ...
;             for (int m = 0; m < 4; ++m) { const int row = row0 + ai * HALF + m * 16; const float rs = rs_of(sum16_fq(E.ss_in + (size_t)row * 16, fq), 1.f / 1024.f);
; #pragma unroll
;                 for (int bj = 0; bj < 2; ++bj) { const int col = col0 + bj * HALF; const f32x4 v0 = acc[ai][bj][m][0] * rs, v1 = acc[ai][bj][m][1] * rs;
;                     if (col < 5120) { u32x4 w; w.x = pk2(v0[0], v0[1]); w.y = pk2(v0[2], v0[3]); w.z = pk2(v1[0], v1[1]); w.w = pk2(v1[2], v1[3]);
;                         if (col < 2048) *(u32x4*)(E.o0 + (size_t)row * 2048 + col) = w; else *(u32x4*)(E.o1 + (size_t)row * 3072 + (col - 2048)) = w; }
;                     else if (col < 5152) { float* tp = E.f0 + (size_t)row * 32 + (col - 5120); *(f32x4*)tp = v0; *(f32x4*)(tp + 4) = v1; } } }
.LBB0_604:
	s_or_b64 exec, exec, s[18:19]
	v_add_u32_e32 v144, 0x90, v172
	v_ashrrev_i32_e32 v145, 31, v144
	v_lshlrev_b64 v[130:131], 6, v[144:145]
	v_lshl_add_u64 v[130:131], v[138:139], 0, v[130:131]
	v_mov_b32_e32 v130, v236
	v_mov_b32_e32 v131, v237
	v_mov_b32_e32 v132, v238
	v_mov_b32_e32 v133, v239
	v_mov_b32_e32 v134, v131
	v_mov_b32_e32 v135, v132
	v_mov_b32_e32 v131, v133
	v_pk_add_f32 v[130:131], v[134:135], v[130:131]
	s_nop 0
	v_add_f32_e32 v130, v130, v131
	ds_bpermute_b32 v131, v148, v130
	s_waitcnt lgkmcnt(0)
	v_add_f32_e32 v130, v130, v131
	ds_bpermute_b32 v131, v149, v130
	s_waitcnt lgkmcnt(0)
	v_add_f32_e32 v130, v130, v131
	v_fmamk_f32 v130, v130, 0x3a800000, v185
	v_rsq_f32_e32 v142, v130
	v_lshlrev_b64 v[130:131], 7, v[144:145]
	v_lshl_add_u64 v[140:141], s[16:17], 0, v[130:131]
	v_pk_mul_f32 v[132:133], v[48:49], v[142:143] op_sel_hi:[1,0]
	v_pk_mul_f32 v[130:131], v[46:47], v[142:143] op_sel_hi:[1,0]
	v_pk_mul_f32 v[136:137], v[44:45], v[142:143] op_sel_hi:[1,0]
	v_pk_mul_f32 v[134:135], v[42:43], v[142:143] op_sel_hi:[1,0]
	s_and_saveexec_b64 s[18:19], s[42:43]
	s_xor_b64 s[18:19], exec, s[18:19]
	s_cbranch_execz .LBB0_607
	s_cmpk_gt_u32 s93, 0x141f
	s_cbranch_scc1 .LBB0_607
	v_mov_b32_e32 v175, v25
	v_lshl_add_u64 v[146:147], v[174:175], 2, v[140:141]
	v_add_co_u32_e32 v150, vcc, 0xffffb000, v146
	s_nop 1
	v_addc_co_u32_e32 v151, vcc, -1, v147, vcc
	global_store_dwordx4 v[150:151], v[130:133], off
	s_nop 1
	v_add_co_u32_e32 v130, vcc, 0xffffc000, v146
	s_nop 1
	v_addc_co_u32_e32 v131, vcc, -1, v147, vcc
	global_store_dwordx4 v[130:131], v[134:137], off offset:-4080

; DI unsigned pk2(float lo, float hi) { const f32x2v v = {lo, hi}; const bf16x2v b = __builtin_convertvector(v, bf16x2v); return __builtin_bit_cast(unsigned, b); }
; DI float rs_of(float ss, float inv_n) { return __builtin_amdgcn_rsqf(ss * inv_n + EPS); }
; DI float sum16_fq(const float* p, int fq) { const f32x4 a = *(const f32x4*)(p + 4 * fq); float s = (a[0] + a[1]) + (a[2] + a[3]); s += __shfl_xor(s, 16); s += __shfl_xor(s, 32); return s; }
; DI void epilogue(int kind, int l, const f32x4 (&acc)[2][2][4][2], const Unit& u, int wr, int wc, int fr, int fq) {
;     ...
;             for (int m = 0; m < 4; ++m) { const int row = row0 + ai * HALF + m * 16; const float rs = rs_of(sum16_fq(E.ss_in + (size_t)row * 16, fq), 1.f / 1024.f);
; #pragma unroll
;                 for (int bj = 0; bj < 2; ++bj) { const int col = col0 + bj * HALF; const f32x4 v0 = acc[ai][bj][m][0] * rs, v1 = acc[ai][bj][m][1] * rs;
;                     if (col < 5120) { u32x4 w; w.x = pk2(v0[0], v0[1]); w.y = pk2(v0[2], v0[3]); w.z = pk2(v1[0], v1[1]); w.w = pk2(v1[2], v1[3]);
;                         if (col < 2048) *(u32x4*)(E.o0 + (size_t)row * 2048 + col) = w; else *(u32x4*)(E.o1 + (size_t)row * 3072 + (col - 2048)) = w; }
;                     else if (col < 5152) { float* tp = E.f0 + (size_t)row * 32 + (col - 5120); *(f32x4*)tp = v0; *(f32x4*)(tp + 4) = v1; } } }
.LBB0_623:
	s_or_b64 exec, exec, s[18:19]
	v_add_u32_e32 v144, 0xa0, v172
	v_ashrrev_i32_e32 v145, 31, v144
	v_lshlrev_b64 v[130:131], 6, v[144:145]
	v_lshl_add_u64 v[130:131], v[138:139], 0, v[130:131]
	v_mov_b32_e32 v130, v240
	v_mov_b32_e32 v131, v241
	v_mov_b32_e32 v132, v242
	v_mov_b32_e32 v133, v243
	v_mov_b32_e32 v134, v131
	v_mov_b32_e32 v135, v132
	v_mov_b32_e32 v131, v133
	v_pk_add_f32 v[130:131], v[134:135], v[130:131]
	s_nop 0
	v_add_f32_e32 v130, v130, v131
	ds_bpermute_b32 v131, v148, v130
	s_waitcnt lgkmcnt(0)
	v_add_f32_e32 v130, v130, v131
	ds_bpermute_b32 v131, v149, v130
	s_waitcnt lgkmcnt(0)
	v_add_f32_e32 v130, v130, v131
	v_fmamk_f32 v130, v130, 0x3a800000, v185
	v_rsq_f32_e32 v142, v130
	v_lshlrev_b64 v[130:131], 7, v[144:145]
	v_lshl_add_u64 v[140:141], s[16:17], 0, v[130:131]
	v_pk_mul_f32 v[132:133], v[32:33], v[142:143] op_sel_hi:[1,0]
	v_pk_mul_f32 v[130:131], v[30:31], v[142:143] op_sel_hi:[1,0]
	v_pk_mul_f32 v[136:137], v[28:29], v[142:143] op_sel_hi:[1,0]
	v_pk_mul_f32 v[134:135], v[26:27], v[142:143] op_sel_hi:[1,0]
	s_and_saveexec_b64 s[18:19], s[42:43]
	s_xor_b64 s[18:19], exec, s[18:19]
	s_cbranch_execz .LBB0_626
	s_cmpk_gt_u32 s93, 0x141f
	s_cbranch_scc1 .LBB0_626
	v_mov_b32_e32 v175, v25
	v_lshl_add_u64 v[146:147], v[174:175], 2, v[140:141]
	v_add_co_u32_e32 v150, vcc, 0xffffb000, v146
	s_nop 1
	v_addc_co_u32_e32 v151, vcc, -1, v147, vcc
	global_store_dwordx4 v[150:151], v[130:133], off
	s_nop 1
	v_add_co_u32_e32 v130, vcc, 0xffffc000, v146
	s_nop 1
	v_addc_co_u32_e32 v131, vcc, -1, v147, vcc
	global_store_dwordx4 v[130:131], v[134:137], off offset:-4080

; DI unsigned pk2(float lo, float hi) { const f32x2v v = {lo, hi}; const bf16x2v b = __builtin_convertvector(v, bf16x2v); return __builtin_bit_cast(unsigned, b); }
; DI float rs_of(float ss, float inv_n) { return __builtin_amdgcn_rsqf(ss * inv_n + EPS); }
; DI float sum16_fq(const float* p, int fq) { const f32x4 a = *(const f32x4*)(p + 4 * fq); float s = (a[0] + a[1]) + (a[2] + a[3]); s += __shfl_xor(s, 16); s += __shfl_xor(s, 32); return s; }
; DI void epilogue(int kind, int l, const f32x4 (&acc)[2][2][4][2], const Unit& u, int wr, int wc, int fr, int fq) {
;     ...
;             for (int m = 0; m < 4; ++m) { const int row = row0 + ai * HALF + m * 16; const float rs = rs_of(sum16_fq(E.ss_in + (size_t)row * 16, fq), 1.f / 1024.f);
; #pragma unroll
;                 for (int bj = 0; bj < 2; ++bj) { const int col = col0 + bj * HALF; const f32x4 v0 = acc[ai][bj][m][0] * rs, v1 = acc[ai][bj][m][1] * rs;
;                     if (col < 5120) { u32x4 w; w.x = pk2(v0[0], v0[1]); w.y = pk2(v0[2], v0[3]); w.z = pk2(v1[0], v1[1]); w.w = pk2(v1[2], v1[3]);
;                         if (col < 2048) *(u32x4*)(E.o0 + (size_t)row * 2048 + col) = w; else *(u32x4*)(E.o1 + (size_t)row * 3072 + (col - 2048)) = w; }
;                     else if (col < 5152) { float* tp = E.f0 + (size_t)row * 32 + (col - 5120); *(f32x4*)tp = v0; *(f32x4*)(tp + 4) = v1; } } }
.LBB0_642:
	s_or_b64 exec, exec, s[18:19]
	v_add_u32_e32 v140, 0xb0, v172
	v_ashrrev_i32_e32 v141, 31, v140
	v_lshlrev_b64 v[130:131], 6, v[140:141]
	v_lshl_add_u64 v[130:131], v[138:139], 0, v[130:131]
	v_mov_b32_e32 v130, v244
	v_mov_b32_e32 v131, v245
	v_mov_b32_e32 v132, v246
	v_mov_b32_e32 v133, v247
	v_mov_b32_e32 v134, v131
	v_mov_b32_e32 v135, v132
	v_mov_b32_e32 v131, v133
	v_pk_add_f32 v[130:131], v[134:135], v[130:131]
	s_nop 0
	v_add_f32_e32 v130, v130, v131
	ds_bpermute_b32 v131, v148, v130
	s_waitcnt lgkmcnt(0)
	v_add_f32_e32 v130, v130, v131
	ds_bpermute_b32 v131, v149, v130
	s_waitcnt lgkmcnt(0)
	v_add_f32_e32 v130, v130, v131
	v_fmamk_f32 v130, v130, 0x3a800000, v185
	v_rsq_f32_e32 v142, v130
	v_lshlrev_b64 v[130:131], 7, v[140:141]
	v_lshl_add_u64 v[138:139], s[16:17], 0, v[130:131]
	v_pk_mul_f32 v[132:133], v[14:15], v[142:143] op_sel_hi:[1,0]
	v_pk_mul_f32 v[130:131], v[12:13], v[142:143] op_sel_hi:[1,0]
	v_pk_mul_f32 v[136:137], v[10:11], v[142:143] op_sel_hi:[1,0]
	v_pk_mul_f32 v[134:135], v[8:9], v[142:143] op_sel_hi:[1,0]
	s_and_saveexec_b64 s[16:17], s[42:43]
	s_xor_b64 s[16:17], exec, s[16:17]
	s_cbranch_execz .LBB0_645
	s_cmpk_gt_u32 s93, 0x141f
	s_cbranch_scc1 .LBB0_645
	v_mov_b32_e32 v175, v25
	v_lshl_add_u64 v[144:145], v[174:175], 2, v[138:139]
	v_add_co_u32_e32 v146, vcc, 0xffffb000, v144
	s_nop 1
	v_addc_co_u32_e32 v147, vcc, -1, v145, vcc
	global_store_dwordx4 v[146:147], v[130:133], off
	s_nop 1
	v_add_co_u32_e32 v130, vcc, 0xffffc000, v144
	s_nop 1
	v_addc_co_u32_e32 v131, vcc, -1, v145, vcc
	global_store_dwordx4 v[130:131], v[134:137], off offset:-4080
